# gdn prep forward substitution rewritten by hand: LOW rows read 3 rows ahead, one fma + DPP add + select on the serial chain (on top of v29)
# speedup vs baseline: 1.0025x; 1.0019x over previous
; #define LAS __attribute__((address_space(3)))
; __device__ __forceinline__ unsigned f2bf(float f) { unsigned u = __builtin_bit_cast(unsigned, f); return (u + 0x7fffu + ((u >> 16) & 1u)) >> 16; }
; __device__ __forceinline__ void gdn_prep_unit(Frame& F, int chain, int ci, unsigned char* rec, float* EGp, unsigned* qctr) {
;     ...
;     if (F.wave < 2) {
;         const int hh2 = lane & 1, j = 32 * F.wave + (lane >> 1);
;         LAS unsigned char* Lrow = (LAS unsigned char*)LOW + hh2 * 16;
;         float Tm[8][4];
; #pragma unroll
;         for (int k = 0; k < 8; ++k) { Tm[k][0] = 0.f; Tm[k][1] = 0.f; Tm[k][2] = 0.f; Tm[k][3] = 0.f; }
; #pragma unroll
;         for (int c = 0; c < 64; ++c) {
;             float a0 = 0.f, a1 = 0.f, a2 = 0.f, a3 = 0.f;
; #pragma unroll
;             for (int k = 0; k < ((c + 3) / 4 + 1) / 2; ++k) { const f32x4 l4 = *(const LAS f32x4*)(Lrow + c * 256 + k * 32);
;                 a0 += l4.x * Tm[k][0]; a1 += l4.y * Tm[k][1]; a2 += l4.z * Tm[k][2]; a3 += l4.w * Tm[k][3]; }
;             float a = (a0 + a1) + (a2 + a3);
;             a += __builtin_bit_cast(float, __builtin_amdgcn_update_dpp(0, __builtin_bit_cast(int, a), 0xB1, 0xF, 0xF, false));
;             const float tn = ((c == j) ? 1.f : 0.f) - a;
;             Tm[c >> 3][c & 3] = (((c >> 2) & 1) == hh2) ? tn : Tm[c >> 3][c & 3];
;             if (hh2 == 0) *(LAS bf16*)(L + PL_TT + c * 144 + j * 2) = (bf16)f2bf(tn);
;         }
;         if (F.wave == 0) F.MISC[16] = 1u;
;     }
.LBB0_1160:
	s_andn2_b64 vcc, exec, s[48:49]
	s_waitcnt lgkmcnt(0)
	s_barrier
	s_cbranch_vccnz .LBB0_1291
	v_and_b32_e32 v2, 1, v88
	v_lshrrev_b32_e32 v3, 1, v88
	v_add_u32_e32 v3, s70, v3
	v_lshl_add_u32 v4, v2, 4, v201
	v_lshlrev_b32_e32 v5, 1, v3
	v_add3_u32 v5, v201, v5, s85
	s_mov_b32 s98, 0x55555555
	s_mov_b32 s99, 0x55555555
	s_mov_b32 s100, 0xaaaaaaaa
	s_mov_b32 s101, 0xaaaaaaaa
	ds_read_b128 v[202:205], v4 offset:256
	ds_read_b128 v[166:169], v4 offset:512
	v_cndmask_b32_e64 v6, -1, v3, s[98:99]
	v_mov_b32_e32 v102, 0
	v_mov_b32_e32 v103, 0
	v_mov_b32_e32 v104, 0
	v_mov_b32_e32 v105, 0
	v_mov_b32_e32 v106, 0
	v_mov_b32_e32 v107, 0
	v_mov_b32_e32 v108, 0
	v_mov_b32_e32 v109, 0
	v_mov_b32_e32 v110, 0
	v_mov_b32_e32 v111, 0
	v_mov_b32_e32 v112, 0
	v_mov_b32_e32 v113, 0
	v_mov_b32_e32 v114, 0
	v_mov_b32_e32 v115, 0
	v_mov_b32_e32 v116, 0
	v_mov_b32_e32 v117, 0
	v_mov_b32_e32 v118, 0
	v_mov_b32_e32 v119, 0
	v_mov_b32_e32 v120, 0
	v_mov_b32_e32 v121, 0
	v_mov_b32_e32 v122, 0
	v_mov_b32_e32 v123, 0
	v_mov_b32_e32 v124, 0
	v_mov_b32_e32 v125, 0
	v_mov_b32_e32 v126, 0
	v_mov_b32_e32 v127, 0
	v_mov_b32_e32 v128, 0
	v_mov_b32_e32 v129, 0
	v_mov_b32_e32 v130, 0
	v_mov_b32_e32 v131, 0
	v_mov_b32_e32 v132, 0
	v_mov_b32_e32 v133, 0
	v_cmp_eq_u32_e64 s[8:9], 0, v6
	s_nop 1
	v_cndmask_b32_e64 v9, 0, -1.0, s[8:9]
	v_sub_f32_e32 v7, 0, v9
	ds_read_b128 v[134:137], v4 offset:768
	s_waitcnt lgkmcnt(2)
	v_cmp_eq_u32_e64 s[8:9], 1, v6
	v_mul_f32_e32 v12, v203, v103
	v_fmac_f32_e32 v12, v205, v105
	v_cndmask_b32_e64 v11, 0, -1.0, s[8:9]
	v_fmac_f32_e32 v11, v204, v104
	v_add_f32_e32 v11, v11, v12
	v_add_f32_dpp v8, v7, v7 quad_perm:[1,0,3,2] row_mask:0xf bank_mask:0xf
	v_cndmask_b32_e64 v102, v102, v8, s[98:99]
	v_cvt_pk_bf16_f32 v8, v8, v8
	ds_write_b16 v5, v8 offset:0
	v_fma_f32 v7, -v202, v102, -v11
	ds_read_b128 v[202:205], v4 offset:1024
	s_waitcnt lgkmcnt(3)
	v_cmp_eq_u32_e64 s[8:9], 2, v6
	v_mul_f32_e32 v10, v166, v102
	v_fmac_f32_e32 v10, v169, v105
	v_cndmask_b32_e64 v9, 0, -1.0, s[8:9]
	v_fmac_f32_e32 v9, v168, v104
	v_add_f32_e32 v9, v9, v10
	v_add_f32_dpp v8, v7, v7 quad_perm:[1,0,3,2] row_mask:0xf bank_mask:0xf
	v_cndmask_b32_e64 v103, v103, v8, s[98:99]
	v_cvt_pk_bf16_f32 v8, v8, v8
	ds_write_b16 v5, v8 offset:144
	v_fma_f32 v7, -v167, v103, -v9
	ds_read_b128 v[166:169], v4 offset:1280
	s_waitcnt lgkmcnt(4)
	v_cmp_eq_u32_e64 s[8:9], 3, v6
	v_mul_f32_e32 v12, v134, v102
	v_fmac_f32_e32 v12, v137, v105
	v_cndmask_b32_e64 v11, 0, -1.0, s[8:9]
	v_fmac_f32_e32 v11, v135, v103
	v_add_f32_e32 v11, v11, v12
	v_add_f32_dpp v8, v7, v7 quad_perm:[1,0,3,2] row_mask:0xf bank_mask:0xf
	v_cndmask_b32_e64 v104, v104, v8, s[98:99]
	v_cvt_pk_bf16_f32 v8, v8, v8
	ds_write_b16 v5, v8 offset:288
	v_fma_f32 v7, -v136, v104, -v11
	ds_read_b128 v[134:137], v4 offset:1536
	s_waitcnt lgkmcnt(4)
	v_cmp_eq_u32_e64 s[8:9], 4, v6
	v_mul_f32_e32 v10, v202, v102
	v_fmac_f32_e32 v10, v204, v104
	v_cndmask_b32_e64 v9, 0, -1.0, s[8:9]
	v_fmac_f32_e32 v9, v203, v103
	v_add_f32_e32 v9, v9, v10
	v_add_f32_dpp v8, v7, v7 quad_perm:[1,0,3,2] row_mask:0xf bank_mask:0xf
	v_cndmask_b32_e64 v105, v105, v8, s[98:99]
	v_cvt_pk_bf16_f32 v8, v8, v8
	ds_write_b16 v5, v8 offset:432
	v_fma_f32 v7, -v205, v105, -v9
	ds_read_b128 v[202:205], v4 offset:1792
	s_waitcnt lgkmcnt(4)
	v_cmp_eq_u32_e64 s[8:9], 5, v6
	v_mul_f32_e32 v12, v167, v103
	v_fmac_f32_e32 v12, v169, v105
	v_cndmask_b32_e64 v11, 0, -1.0, s[8:9]
	v_fmac_f32_e32 v11, v168, v104
	v_add_f32_e32 v11, v11, v12
	v_add_f32_dpp v8, v7, v7 quad_perm:[1,0,3,2] row_mask:0xf bank_mask:0xf
	v_cndmask_b32_e64 v102, v102, v8, s[100:101]
	v_cvt_pk_bf16_f32 v8, v8, v8
	ds_write_b16 v5, v8 offset:576
	v_fma_f32 v7, -v166, v102, -v11
	ds_read_b128 v[166:169], v4 offset:2048
	s_waitcnt lgkmcnt(4)
	v_cmp_eq_u32_e64 s[8:9], 6, v6
	v_mul_f32_e32 v10, v134, v102
	v_fmac_f32_e32 v10, v137, v105
	v_cndmask_b32_e64 v9, 0, -1.0, s[8:9]
	v_fmac_f32_e32 v9, v136, v104
	v_add_f32_e32 v9, v9, v10
	v_add_f32_dpp v8, v7, v7 quad_perm:[1,0,3,2] row_mask:0xf bank_mask:0xf
	v_cndmask_b32_e64 v103, v103, v8, s[100:101]
	v_cvt_pk_bf16_f32 v8, v8, v8
	ds_write_b16 v5, v8 offset:720
	v_fma_f32 v7, -v135, v103, -v9
	ds_read_b128 v[134:137], v4 offset:2304
	ds_read_b128 v[138:141], v4 offset:2336
	s_waitcnt lgkmcnt(5)
	v_cmp_eq_u32_e64 s[8:9], 7, v6
	v_mul_f32_e32 v12, v202, v102
	v_fmac_f32_e32 v12, v205, v105
	v_cndmask_b32_e64 v11, 0, -1.0, s[8:9]
	v_fmac_f32_e32 v11, v203, v103
	v_add_f32_e32 v11, v11, v12
	v_add_f32_dpp v8, v7, v7 quad_perm:[1,0,3,2] row_mask:0xf bank_mask:0xf
	v_cndmask_b32_e64 v104, v104, v8, s[100:101]
	v_cvt_pk_bf16_f32 v8, v8, v8
	ds_write_b16 v5, v8 offset:864
	v_fma_f32 v7, -v204, v104, -v11
	ds_read_b128 v[202:205], v4 offset:2560
	ds_read_b128 v[206:209], v4 offset:2592
	s_waitcnt lgkmcnt(6)
	v_cmp_eq_u32_e64 s[8:9], 8, v6
	v_mul_f32_e32 v10, v166, v102
	v_fmac_f32_e32 v10, v168, v104
	v_cndmask_b32_e64 v9, 0, -1.0, s[8:9]
	v_fmac_f32_e32 v9, v167, v103
	v_add_f32_e32 v9, v9, v10
	v_add_f32_dpp v8, v7, v7 quad_perm:[1,0,3,2] row_mask:0xf bank_mask:0xf
	v_cndmask_b32_e64 v105, v105, v8, s[100:101]
	v_cvt_pk_bf16_f32 v8, v8, v8
	ds_write_b16 v5, v8 offset:1008
	v_fma_f32 v7, -v169, v105, -v9
	ds_read_b128 v[166:169], v4 offset:2816
	ds_read_b128 v[170:173], v4 offset:2848
	s_waitcnt lgkmcnt(6)
	v_cmp_eq_u32_e64 s[8:9], 9, v6
	v_mul_f32_e32 v12, v134, v102
	v_fmac_f32_e32 v12, v136, v104
	v_fmac_f32_e32 v12, v139, v107
	v_fmac_f32_e32 v12, v141, v109
	v_cndmask_b32_e64 v11, 0, -1.0, s[8:9]
	v_fmac_f32_e32 v11, v135, v103
	v_fmac_f32_e32 v11, v137, v105
	v_fmac_f32_e32 v11, v140, v108
	v_add_f32_e32 v11, v11, v12
	v_add_f32_dpp v8, v7, v7 quad_perm:[1,0,3,2] row_mask:0xf bank_mask:0xf
	v_cndmask_b32_e64 v106, v106, v8, s[98:99]
	v_cvt_pk_bf16_f32 v8, v8, v8
	ds_write_b16 v5, v8 offset:1152
	v_fma_f32 v7, -v138, v106, -v11
	ds_read_b128 v[134:137], v4 offset:3072
	ds_read_b128 v[138:141], v4 offset:3104
	s_waitcnt lgkmcnt(6)
; #define LAS __attribute__((address_space(3)))
; __device__ __forceinline__ unsigned f2bf(float f) { unsigned u = __builtin_bit_cast(unsigned, f); return (u + 0x7fffu + ((u >> 16) & 1u)) >> 16; }
; __device__ __forceinline__ void gdn_prep_unit(Frame& F, int chain, int ci, unsigned char* rec, float* EGp, unsigned* qctr) {
;     ...
;         for (int c = 0; c < 64; ++c) {
;             float a0 = 0.f, a1 = 0.f, a2 = 0.f, a3 = 0.f;
; #pragma unroll
;             for (int k = 0; k < ((c + 3) / 4 + 1) / 2; ++k) { const f32x4 l4 = *(const LAS f32x4*)(Lrow + c * 256 + k * 32);
;                 a0 += l4.x * Tm[k][0]; a1 += l4.y * Tm[k][1]; a2 += l4.z * Tm[k][2]; a3 += l4.w * Tm[k][3]; }
;             float a = (a0 + a1) + (a2 + a3);
;             a += __builtin_bit_cast(float, __builtin_amdgcn_update_dpp(0, __builtin_bit_cast(int, a), 0xB1, 0xF, 0xF, false));
;             const float tn = ((c == j) ? 1.f : 0.f) - a;
;             Tm[c >> 3][c & 3] = (((c >> 2) & 1) == hh2) ? tn : Tm[c >> 3][c & 3];
;             if (hh2 == 0) *(LAS bf16*)(L + PL_TT + c * 144 + j * 2) = (bf16)f2bf(tn);
;         }
	v_cmp_eq_u32_e64 s[8:9], 10, v6
	v_mul_f32_e32 v10, v202, v102
	v_fmac_f32_e32 v10, v204, v104
	v_fmac_f32_e32 v10, v206, v106
	v_fmac_f32_e32 v10, v209, v109
	v_cndmask_b32_e64 v9, 0, -1.0, s[8:9]
	v_fmac_f32_e32 v9, v203, v103
	v_fmac_f32_e32 v9, v205, v105
	v_fmac_f32_e32 v9, v208, v108
	v_add_f32_e32 v9, v9, v10
	v_add_f32_dpp v8, v7, v7 quad_perm:[1,0,3,2] row_mask:0xf bank_mask:0xf
	v_cndmask_b32_e64 v107, v107, v8, s[98:99]
	v_cvt_pk_bf16_f32 v8, v8, v8
	ds_write_b16 v5, v8 offset:1296
	v_fma_f32 v7, -v207, v107, -v9
	ds_read_b128 v[202:205], v4 offset:3328
	ds_read_b128 v[206:209], v4 offset:3360
	s_waitcnt lgkmcnt(6)
	v_cmp_eq_u32_e64 s[8:9], 11, v6
	v_mul_f32_e32 v12, v166, v102
	v_fmac_f32_e32 v12, v168, v104
	v_fmac_f32_e32 v12, v170, v106
	v_fmac_f32_e32 v12, v173, v109
	v_cndmask_b32_e64 v11, 0, -1.0, s[8:9]
	v_fmac_f32_e32 v11, v167, v103
	v_fmac_f32_e32 v11, v169, v105
	v_fmac_f32_e32 v11, v171, v107
	v_add_f32_e32 v11, v11, v12
	v_add_f32_dpp v8, v7, v7 quad_perm:[1,0,3,2] row_mask:0xf bank_mask:0xf
	v_cndmask_b32_e64 v108, v108, v8, s[98:99]
	v_cvt_pk_bf16_f32 v8, v8, v8
	ds_write_b16 v5, v8 offset:1440
	v_fma_f32 v7, -v172, v108, -v11
	ds_read_b128 v[166:169], v4 offset:3584
	ds_read_b128 v[170:173], v4 offset:3616
	s_waitcnt lgkmcnt(6)
	v_cmp_eq_u32_e64 s[8:9], 12, v6
	v_mul_f32_e32 v10, v134, v102
	v_fmac_f32_e32 v10, v136, v104
	v_fmac_f32_e32 v10, v138, v106
	v_fmac_f32_e32 v10, v140, v108
	v_cndmask_b32_e64 v9, 0, -1.0, s[8:9]
	v_fmac_f32_e32 v9, v135, v103
	v_fmac_f32_e32 v9, v137, v105
	v_fmac_f32_e32 v9, v139, v107
	v_add_f32_e32 v9, v9, v10
	v_add_f32_dpp v8, v7, v7 quad_perm:[1,0,3,2] row_mask:0xf bank_mask:0xf
	v_cndmask_b32_e64 v109, v109, v8, s[98:99]
	v_cvt_pk_bf16_f32 v8, v8, v8
	ds_write_b16 v5, v8 offset:1584
	v_fma_f32 v7, -v141, v109, -v9
	ds_read_b128 v[134:137], v4 offset:3840
	ds_read_b128 v[138:141], v4 offset:3872
	s_waitcnt lgkmcnt(6)
	v_cmp_eq_u32_e64 s[8:9], 13, v6
	v_mul_f32_e32 v12, v202, v102
	v_fmac_f32_e32 v12, v204, v104
	v_fmac_f32_e32 v12, v207, v107
	v_fmac_f32_e32 v12, v209, v109
	v_cndmask_b32_e64 v11, 0, -1.0, s[8:9]
	v_fmac_f32_e32 v11, v203, v103
	v_fmac_f32_e32 v11, v205, v105
	v_fmac_f32_e32 v11, v208, v108
	v_add_f32_e32 v11, v11, v12
	v_add_f32_dpp v8, v7, v7 quad_perm:[1,0,3,2] row_mask:0xf bank_mask:0xf
	v_cndmask_b32_e64 v106, v106, v8, s[100:101]
	v_cvt_pk_bf16_f32 v8, v8, v8
	ds_write_b16 v5, v8 offset:1728
	v_fma_f32 v7, -v206, v106, -v11
	ds_read_b128 v[202:205], v4 offset:4096
	ds_read_b128 v[206:209], v4 offset:4128
	s_waitcnt lgkmcnt(6)
	v_cmp_eq_u32_e64 s[8:9], 14, v6
	v_mul_f32_e32 v10, v166, v102
	v_fmac_f32_e32 v10, v168, v104
	v_fmac_f32_e32 v10, v170, v106
	v_fmac_f32_e32 v10, v173, v109
	v_cndmask_b32_e64 v9, 0, -1.0, s[8:9]
	v_fmac_f32_e32 v9, v167, v103
	v_fmac_f32_e32 v9, v169, v105
	v_fmac_f32_e32 v9, v172, v108
	v_add_f32_e32 v9, v9, v10
	v_add_f32_dpp v8, v7, v7 quad_perm:[1,0,3,2] row_mask:0xf bank_mask:0xf
	v_cndmask_b32_e64 v107, v107, v8, s[100:101]
	v_cvt_pk_bf16_f32 v8, v8, v8
	ds_write_b16 v5, v8 offset:1872
	v_fma_f32 v7, -v171, v107, -v9
	ds_read_b128 v[166:169], v4 offset:4352
	ds_read_b128 v[170:173], v4 offset:4384
	ds_read_b128 v[174:177], v4 offset:4416
	s_waitcnt lgkmcnt(7)
	v_cmp_eq_u32_e64 s[8:9], 15, v6
	v_mul_f32_e32 v12, v134, v102
	v_fmac_f32_e32 v12, v136, v104
	v_fmac_f32_e32 v12, v138, v106
	v_fmac_f32_e32 v12, v141, v109
	v_cndmask_b32_e64 v11, 0, -1.0, s[8:9]
	v_fmac_f32_e32 v11, v135, v103
	v_fmac_f32_e32 v11, v137, v105
	v_fmac_f32_e32 v11, v139, v107
	v_add_f32_e32 v11, v11, v12
	v_add_f32_dpp v8, v7, v7 quad_perm:[1,0,3,2] row_mask:0xf bank_mask:0xf
	v_cndmask_b32_e64 v108, v108, v8, s[100:101]
	v_cvt_pk_bf16_f32 v8, v8, v8
	ds_write_b16 v5, v8 offset:2016
	v_fma_f32 v7, -v140, v108, -v11
	ds_read_b128 v[134:137], v4 offset:4608
	ds_read_b128 v[138:141], v4 offset:4640
	ds_read_b128 v[142:145], v4 offset:4672
	s_waitcnt lgkmcnt(8)
	v_cmp_eq_u32_e64 s[8:9], 16, v6
	v_mul_f32_e32 v10, v202, v102
	v_fmac_f32_e32 v10, v204, v104
	v_fmac_f32_e32 v10, v206, v106
	v_fmac_f32_e32 v10, v208, v108
	v_cndmask_b32_e64 v9, 0, -1.0, s[8:9]
	v_fmac_f32_e32 v9, v203, v103
	v_fmac_f32_e32 v9, v205, v105
	v_fmac_f32_e32 v9, v207, v107
	v_add_f32_e32 v9, v9, v10
	v_add_f32_dpp v8, v7, v7 quad_perm:[1,0,3,2] row_mask:0xf bank_mask:0xf
	v_cndmask_b32_e64 v109, v109, v8, s[100:101]
	v_cvt_pk_bf16_f32 v8, v8, v8
	ds_write_b16 v5, v8 offset:2160
	v_fma_f32 v7, -v209, v109, -v9
	ds_read_b128 v[202:205], v4 offset:4864
	ds_read_b128 v[206:209], v4 offset:4896
	ds_read_b128 v[210:213], v4 offset:4928
	s_waitcnt lgkmcnt(8)
	v_cmp_eq_u32_e64 s[8:9], 17, v6
	v_mul_f32_e32 v12, v166, v102
	v_fmac_f32_e32 v12, v168, v104
	v_fmac_f32_e32 v12, v170, v106
	v_fmac_f32_e32 v12, v172, v108
	v_fmac_f32_e32 v12, v175, v111
	v_fmac_f32_e32 v12, v177, v113
	v_cndmask_b32_e64 v11, 0, -1.0, s[8:9]
	v_fmac_f32_e32 v11, v167, v103
	v_fmac_f32_e32 v11, v169, v105
	v_fmac_f32_e32 v11, v171, v107
	v_fmac_f32_e32 v11, v173, v109
	v_fmac_f32_e32 v11, v176, v112
	v_add_f32_e32 v11, v11, v12
	v_add_f32_dpp v8, v7, v7 quad_perm:[1,0,3,2] row_mask:0xf bank_mask:0xf
	v_cndmask_b32_e64 v110, v110, v8, s[98:99]
	v_cvt_pk_bf16_f32 v8, v8, v8
	ds_write_b16 v5, v8 offset:2304
	v_fma_f32 v7, -v174, v110, -v11
	ds_read_b128 v[166:169], v4 offset:5120
	ds_read_b128 v[170:173], v4 offset:5152
	ds_read_b128 v[174:177], v4 offset:5184
	s_waitcnt lgkmcnt(8)
; #define LAS __attribute__((address_space(3)))
; __device__ __forceinline__ unsigned f2bf(float f) { unsigned u = __builtin_bit_cast(unsigned, f); return (u + 0x7fffu + ((u >> 16) & 1u)) >> 16; }
; __device__ __forceinline__ void gdn_prep_unit(Frame& F, int chain, int ci, unsigned char* rec, float* EGp, unsigned* qctr) {
;     ...
;         for (int c = 0; c < 64; ++c) {
;             float a0 = 0.f, a1 = 0.f, a2 = 0.f, a3 = 0.f;
; #pragma unroll
;             for (int k = 0; k < ((c + 3) / 4 + 1) / 2; ++k) { const f32x4 l4 = *(const LAS f32x4*)(Lrow + c * 256 + k * 32);
;                 a0 += l4.x * Tm[k][0]; a1 += l4.y * Tm[k][1]; a2 += l4.z * Tm[k][2]; a3 += l4.w * Tm[k][3]; }
;             float a = (a0 + a1) + (a2 + a3);
;             a += __builtin_bit_cast(float, __builtin_amdgcn_update_dpp(0, __builtin_bit_cast(int, a), 0xB1, 0xF, 0xF, false));
;             const float tn = ((c == j) ? 1.f : 0.f) - a;
;             Tm[c >> 3][c & 3] = (((c >> 2) & 1) == hh2) ? tn : Tm[c >> 3][c & 3];
;             if (hh2 == 0) *(LAS bf16*)(L + PL_TT + c * 144 + j * 2) = (bf16)f2bf(tn);
;         }
	v_cmp_eq_u32_e64 s[8:9], 18, v6
	v_mul_f32_e32 v10, v134, v102
	v_fmac_f32_e32 v10, v136, v104
	v_fmac_f32_e32 v10, v138, v106
	v_fmac_f32_e32 v10, v140, v108
	v_fmac_f32_e32 v10, v142, v110
	v_fmac_f32_e32 v10, v145, v113
	v_cndmask_b32_e64 v9, 0, -1.0, s[8:9]
	v_fmac_f32_e32 v9, v135, v103
	v_fmac_f32_e32 v9, v137, v105
	v_fmac_f32_e32 v9, v139, v107
	v_fmac_f32_e32 v9, v141, v109
	v_fmac_f32_e32 v9, v144, v112
	v_add_f32_e32 v9, v9, v10
	v_add_f32_dpp v8, v7, v7 quad_perm:[1,0,3,2] row_mask:0xf bank_mask:0xf
	v_cndmask_b32_e64 v111, v111, v8, s[98:99]
	v_cvt_pk_bf16_f32 v8, v8, v8
	ds_write_b16 v5, v8 offset:2448
	v_fma_f32 v7, -v143, v111, -v9
	ds_read_b128 v[134:137], v4 offset:5376
	ds_read_b128 v[138:141], v4 offset:5408
	ds_read_b128 v[142:145], v4 offset:5440
	s_waitcnt lgkmcnt(8)
	v_cmp_eq_u32_e64 s[8:9], 19, v6
	v_mul_f32_e32 v12, v202, v102
	v_fmac_f32_e32 v12, v204, v104
	v_fmac_f32_e32 v12, v206, v106
	v_fmac_f32_e32 v12, v208, v108
	v_fmac_f32_e32 v12, v210, v110
	v_fmac_f32_e32 v12, v213, v113
	v_cndmask_b32_e64 v11, 0, -1.0, s[8:9]
	v_fmac_f32_e32 v11, v203, v103
	v_fmac_f32_e32 v11, v205, v105
	v_fmac_f32_e32 v11, v207, v107
	v_fmac_f32_e32 v11, v209, v109
	v_fmac_f32_e32 v11, v211, v111
	v_add_f32_e32 v11, v11, v12
	v_add_f32_dpp v8, v7, v7 quad_perm:[1,0,3,2] row_mask:0xf bank_mask:0xf
	v_cndmask_b32_e64 v112, v112, v8, s[98:99]
	v_cvt_pk_bf16_f32 v8, v8, v8
	ds_write_b16 v5, v8 offset:2592
	v_fma_f32 v7, -v212, v112, -v11
	ds_read_b128 v[202:205], v4 offset:5632
	ds_read_b128 v[206:209], v4 offset:5664
	ds_read_b128 v[210:213], v4 offset:5696
	s_waitcnt lgkmcnt(8)
	v_cmp_eq_u32_e64 s[8:9], 20, v6
	v_mul_f32_e32 v10, v166, v102
	v_fmac_f32_e32 v10, v168, v104
	v_fmac_f32_e32 v10, v170, v106
	v_fmac_f32_e32 v10, v172, v108
	v_fmac_f32_e32 v10, v174, v110
	v_fmac_f32_e32 v10, v176, v112
	v_cndmask_b32_e64 v9, 0, -1.0, s[8:9]
	v_fmac_f32_e32 v9, v167, v103
	v_fmac_f32_e32 v9, v169, v105
	v_fmac_f32_e32 v9, v171, v107
	v_fmac_f32_e32 v9, v173, v109
	v_fmac_f32_e32 v9, v175, v111
	v_add_f32_e32 v9, v9, v10
	v_add_f32_dpp v8, v7, v7 quad_perm:[1,0,3,2] row_mask:0xf bank_mask:0xf
	v_cndmask_b32_e64 v113, v113, v8, s[98:99]
	v_cvt_pk_bf16_f32 v8, v8, v8
	ds_write_b16 v5, v8 offset:2736
	v_fma_f32 v7, -v177, v113, -v9
	ds_read_b128 v[166:169], v4 offset:5888
	ds_read_b128 v[170:173], v4 offset:5920
	ds_read_b128 v[174:177], v4 offset:5952
	s_waitcnt lgkmcnt(8)
	v_cmp_eq_u32_e64 s[8:9], 21, v6
	v_mul_f32_e32 v12, v134, v102
	v_fmac_f32_e32 v12, v136, v104
	v_fmac_f32_e32 v12, v138, v106
	v_fmac_f32_e32 v12, v140, v108
	v_fmac_f32_e32 v12, v143, v111
	v_fmac_f32_e32 v12, v145, v113
	v_cndmask_b32_e64 v11, 0, -1.0, s[8:9]
	v_fmac_f32_e32 v11, v135, v103
	v_fmac_f32_e32 v11, v137, v105
	v_fmac_f32_e32 v11, v139, v107
	v_fmac_f32_e32 v11, v141, v109
	v_fmac_f32_e32 v11, v144, v112
	v_add_f32_e32 v11, v11, v12
	v_add_f32_dpp v8, v7, v7 quad_perm:[1,0,3,2] row_mask:0xf bank_mask:0xf
	v_cndmask_b32_e64 v110, v110, v8, s[100:101]
	v_cvt_pk_bf16_f32 v8, v8, v8
	ds_write_b16 v5, v8 offset:2880
	v_fma_f32 v7, -v142, v110, -v11
	ds_read_b128 v[134:137], v4 offset:6144
	ds_read_b128 v[138:141], v4 offset:6176
	ds_read_b128 v[142:145], v4 offset:6208
	s_waitcnt lgkmcnt(8)
	v_cmp_eq_u32_e64 s[8:9], 22, v6
	v_mul_f32_e32 v10, v202, v102
	v_fmac_f32_e32 v10, v204, v104
	v_fmac_f32_e32 v10, v206, v106
	v_fmac_f32_e32 v10, v208, v108
	v_fmac_f32_e32 v10, v210, v110
	v_fmac_f32_e32 v10, v213, v113
	v_cndmask_b32_e64 v9, 0, -1.0, s[8:9]
	v_fmac_f32_e32 v9, v203, v103
	v_fmac_f32_e32 v9, v205, v105
	v_fmac_f32_e32 v9, v207, v107
	v_fmac_f32_e32 v9, v209, v109
	v_fmac_f32_e32 v9, v212, v112
	v_add_f32_e32 v9, v9, v10
	v_add_f32_dpp v8, v7, v7 quad_perm:[1,0,3,2] row_mask:0xf bank_mask:0xf
	v_cndmask_b32_e64 v111, v111, v8, s[100:101]
	v_cvt_pk_bf16_f32 v8, v8, v8
	ds_write_b16 v5, v8 offset:3024
	v_fma_f32 v7, -v211, v111, -v9
	ds_read_b128 v[202:205], v4 offset:6400
	ds_read_b128 v[206:209], v4 offset:6432
	ds_read_b128 v[210:213], v4 offset:6464
	ds_read_b128 v[220:223], v4 offset:6496
	s_waitcnt lgkmcnt(9)
	v_cmp_eq_u32_e64 s[8:9], 23, v6
	v_mul_f32_e32 v12, v166, v102
	v_fmac_f32_e32 v12, v168, v104
	v_fmac_f32_e32 v12, v170, v106
	v_fmac_f32_e32 v12, v172, v108
	v_fmac_f32_e32 v12, v174, v110
	v_fmac_f32_e32 v12, v177, v113
	v_cndmask_b32_e64 v11, 0, -1.0, s[8:9]
	v_fmac_f32_e32 v11, v167, v103
	v_fmac_f32_e32 v11, v169, v105
	v_fmac_f32_e32 v11, v171, v107
	v_fmac_f32_e32 v11, v173, v109
	v_fmac_f32_e32 v11, v175, v111
	v_add_f32_e32 v11, v11, v12
	v_add_f32_dpp v8, v7, v7 quad_perm:[1,0,3,2] row_mask:0xf bank_mask:0xf
	v_cndmask_b32_e64 v112, v112, v8, s[100:101]
	v_cvt_pk_bf16_f32 v8, v8, v8
	ds_write_b16 v5, v8 offset:3168
	v_fma_f32 v7, -v176, v112, -v11
	ds_read_b128 v[166:169], v4 offset:6656
	ds_read_b128 v[170:173], v4 offset:6688
	ds_read_b128 v[174:177], v4 offset:6720
	ds_read_b128 v[178:181], v4 offset:6752
	s_waitcnt lgkmcnt(10)
	v_cmp_eq_u32_e64 s[8:9], 24, v6
	v_mul_f32_e32 v10, v134, v102
	v_fmac_f32_e32 v10, v136, v104
	v_fmac_f32_e32 v10, v138, v106
	v_fmac_f32_e32 v10, v140, v108
	v_fmac_f32_e32 v10, v142, v110
	v_fmac_f32_e32 v10, v144, v112
	v_cndmask_b32_e64 v9, 0, -1.0, s[8:9]
	v_fmac_f32_e32 v9, v135, v103
	v_fmac_f32_e32 v9, v137, v105
	v_fmac_f32_e32 v9, v139, v107
	v_fmac_f32_e32 v9, v141, v109
	v_fmac_f32_e32 v9, v143, v111
	v_add_f32_e32 v9, v9, v10
	v_add_f32_dpp v8, v7, v7 quad_perm:[1,0,3,2] row_mask:0xf bank_mask:0xf
	v_cndmask_b32_e64 v113, v113, v8, s[100:101]
	v_cvt_pk_bf16_f32 v8, v8, v8
	ds_write_b16 v5, v8 offset:3312
	v_fma_f32 v7, -v145, v113, -v9
	ds_read_b128 v[134:137], v4 offset:6912
	ds_read_b128 v[138:141], v4 offset:6944
	ds_read_b128 v[142:145], v4 offset:6976
	ds_read_b128 v[146:149], v4 offset:7008
	s_waitcnt lgkmcnt(10)
; #define LAS __attribute__((address_space(3)))
; __device__ __forceinline__ unsigned f2bf(float f) { unsigned u = __builtin_bit_cast(unsigned, f); return (u + 0x7fffu + ((u >> 16) & 1u)) >> 16; }
; __device__ __forceinline__ void gdn_prep_unit(Frame& F, int chain, int ci, unsigned char* rec, float* EGp, unsigned* qctr) {
;     ...
;         for (int c = 0; c < 64; ++c) {
;             float a0 = 0.f, a1 = 0.f, a2 = 0.f, a3 = 0.f;
; #pragma unroll
;             for (int k = 0; k < ((c + 3) / 4 + 1) / 2; ++k) { const f32x4 l4 = *(const LAS f32x4*)(Lrow + c * 256 + k * 32);
;                 a0 += l4.x * Tm[k][0]; a1 += l4.y * Tm[k][1]; a2 += l4.z * Tm[k][2]; a3 += l4.w * Tm[k][3]; }
;             float a = (a0 + a1) + (a2 + a3);
;             a += __builtin_bit_cast(float, __builtin_amdgcn_update_dpp(0, __builtin_bit_cast(int, a), 0xB1, 0xF, 0xF, false));
;             const float tn = ((c == j) ? 1.f : 0.f) - a;
;             Tm[c >> 3][c & 3] = (((c >> 2) & 1) == hh2) ? tn : Tm[c >> 3][c & 3];
;             if (hh2 == 0) *(LAS bf16*)(L + PL_TT + c * 144 + j * 2) = (bf16)f2bf(tn);
;         }
	v_cmp_eq_u32_e64 s[8:9], 25, v6
	v_mul_f32_e32 v12, v202, v102
	v_fmac_f32_e32 v12, v204, v104
	v_fmac_f32_e32 v12, v206, v106
	v_fmac_f32_e32 v12, v208, v108
	v_fmac_f32_e32 v12, v210, v110
	v_fmac_f32_e32 v12, v212, v112
	v_fmac_f32_e32 v12, v221, v115
	v_fmac_f32_e32 v12, v223, v117
	v_cndmask_b32_e64 v11, 0, -1.0, s[8:9]
	v_fmac_f32_e32 v11, v203, v103
	v_fmac_f32_e32 v11, v205, v105
	v_fmac_f32_e32 v11, v207, v107
	v_fmac_f32_e32 v11, v209, v109
	v_fmac_f32_e32 v11, v211, v111
	v_fmac_f32_e32 v11, v213, v113
	v_fmac_f32_e32 v11, v222, v116
	v_add_f32_e32 v11, v11, v12
	v_add_f32_dpp v8, v7, v7 quad_perm:[1,0,3,2] row_mask:0xf bank_mask:0xf
	v_cndmask_b32_e64 v114, v114, v8, s[98:99]
	v_cvt_pk_bf16_f32 v8, v8, v8
	ds_write_b16 v5, v8 offset:3456
	v_fma_f32 v7, -v220, v114, -v11
	ds_read_b128 v[202:205], v4 offset:7168
	ds_read_b128 v[206:209], v4 offset:7200
	ds_read_b128 v[210:213], v4 offset:7232
	ds_read_b128 v[220:223], v4 offset:7264
	s_waitcnt lgkmcnt(10)
	v_cmp_eq_u32_e64 s[8:9], 26, v6
	v_mul_f32_e32 v10, v166, v102
	v_fmac_f32_e32 v10, v168, v104
	v_fmac_f32_e32 v10, v170, v106
	v_fmac_f32_e32 v10, v172, v108
	v_fmac_f32_e32 v10, v174, v110
	v_fmac_f32_e32 v10, v176, v112
	v_fmac_f32_e32 v10, v178, v114
	v_fmac_f32_e32 v10, v181, v117
	v_cndmask_b32_e64 v9, 0, -1.0, s[8:9]
	v_fmac_f32_e32 v9, v167, v103
	v_fmac_f32_e32 v9, v169, v105
	v_fmac_f32_e32 v9, v171, v107
	v_fmac_f32_e32 v9, v173, v109
	v_fmac_f32_e32 v9, v175, v111
	v_fmac_f32_e32 v9, v177, v113
	v_fmac_f32_e32 v9, v180, v116
	v_add_f32_e32 v9, v9, v10
	v_add_f32_dpp v8, v7, v7 quad_perm:[1,0,3,2] row_mask:0xf bank_mask:0xf
	v_cndmask_b32_e64 v115, v115, v8, s[98:99]
	v_cvt_pk_bf16_f32 v8, v8, v8
	ds_write_b16 v5, v8 offset:3600
	v_fma_f32 v7, -v179, v115, -v9
	ds_read_b128 v[166:169], v4 offset:7424
	ds_read_b128 v[170:173], v4 offset:7456
	ds_read_b128 v[174:177], v4 offset:7488
	ds_read_b128 v[178:181], v4 offset:7520
	s_waitcnt lgkmcnt(10)
	v_cmp_eq_u32_e64 s[8:9], 27, v6
	v_mul_f32_e32 v12, v134, v102
	v_fmac_f32_e32 v12, v136, v104
	v_fmac_f32_e32 v12, v138, v106
	v_fmac_f32_e32 v12, v140, v108
	v_fmac_f32_e32 v12, v142, v110
	v_fmac_f32_e32 v12, v144, v112
	v_fmac_f32_e32 v12, v146, v114
	v_fmac_f32_e32 v12, v149, v117
	v_cndmask_b32_e64 v11, 0, -1.0, s[8:9]
	v_fmac_f32_e32 v11, v135, v103
	v_fmac_f32_e32 v11, v137, v105
	v_fmac_f32_e32 v11, v139, v107
	v_fmac_f32_e32 v11, v141, v109
	v_fmac_f32_e32 v11, v143, v111
	v_fmac_f32_e32 v11, v145, v113
	v_fmac_f32_e32 v11, v147, v115
	v_add_f32_e32 v11, v11, v12
	v_add_f32_dpp v8, v7, v7 quad_perm:[1,0,3,2] row_mask:0xf bank_mask:0xf
	v_cndmask_b32_e64 v116, v116, v8, s[98:99]
	v_cvt_pk_bf16_f32 v8, v8, v8
	ds_write_b16 v5, v8 offset:3744
	v_fma_f32 v7, -v148, v116, -v11
	ds_read_b128 v[134:137], v4 offset:7680
	ds_read_b128 v[138:141], v4 offset:7712
	ds_read_b128 v[142:145], v4 offset:7744
	ds_read_b128 v[146:149], v4 offset:7776
	s_waitcnt lgkmcnt(10)
	v_cmp_eq_u32_e64 s[8:9], 28, v6
	v_mul_f32_e32 v10, v202, v102
	v_fmac_f32_e32 v10, v204, v104
	v_fmac_f32_e32 v10, v206, v106
	v_fmac_f32_e32 v10, v208, v108
	v_fmac_f32_e32 v10, v210, v110
	v_fmac_f32_e32 v10, v212, v112
	v_fmac_f32_e32 v10, v220, v114
	v_fmac_f32_e32 v10, v222, v116
	v_cndmask_b32_e64 v9, 0, -1.0, s[8:9]
	v_fmac_f32_e32 v9, v203, v103
	v_fmac_f32_e32 v9, v205, v105
	v_fmac_f32_e32 v9, v207, v107
	v_fmac_f32_e32 v9, v209, v109
	v_fmac_f32_e32 v9, v211, v111
	v_fmac_f32_e32 v9, v213, v113
	v_fmac_f32_e32 v9, v221, v115
	v_add_f32_e32 v9, v9, v10
	v_add_f32_dpp v8, v7, v7 quad_perm:[1,0,3,2] row_mask:0xf bank_mask:0xf
	v_cndmask_b32_e64 v117, v117, v8, s[98:99]
	v_cvt_pk_bf16_f32 v8, v8, v8
	ds_write_b16 v5, v8 offset:3888
	v_fma_f32 v7, -v223, v117, -v9
	ds_read_b128 v[202:205], v4 offset:7936
	ds_read_b128 v[206:209], v4 offset:7968
	ds_read_b128 v[210:213], v4 offset:8000
	ds_read_b128 v[220:223], v4 offset:8032
	s_waitcnt lgkmcnt(10)
	v_cmp_eq_u32_e64 s[8:9], 29, v6
	v_mul_f32_e32 v12, v166, v102
	v_fmac_f32_e32 v12, v168, v104
	v_fmac_f32_e32 v12, v170, v106
	v_fmac_f32_e32 v12, v172, v108
	v_fmac_f32_e32 v12, v174, v110
	v_fmac_f32_e32 v12, v176, v112
	v_fmac_f32_e32 v12, v179, v115
	v_fmac_f32_e32 v12, v181, v117
	v_cndmask_b32_e64 v11, 0, -1.0, s[8:9]
	v_fmac_f32_e32 v11, v167, v103
	v_fmac_f32_e32 v11, v169, v105
	v_fmac_f32_e32 v11, v171, v107
	v_fmac_f32_e32 v11, v173, v109
	v_fmac_f32_e32 v11, v175, v111
	v_fmac_f32_e32 v11, v177, v113
	v_fmac_f32_e32 v11, v180, v116
	v_add_f32_e32 v11, v11, v12
	v_add_f32_dpp v8, v7, v7 quad_perm:[1,0,3,2] row_mask:0xf bank_mask:0xf
	v_cndmask_b32_e64 v114, v114, v8, s[100:101]
	v_cvt_pk_bf16_f32 v8, v8, v8
	ds_write_b16 v5, v8 offset:4032
	v_fma_f32 v7, -v178, v114, -v11
	ds_read_b128 v[166:169], v4 offset:8192
	ds_read_b128 v[170:173], v4 offset:8224
	ds_read_b128 v[174:177], v4 offset:8256
	ds_read_b128 v[178:181], v4 offset:8288
	s_waitcnt lgkmcnt(10)
	v_cmp_eq_u32_e64 s[8:9], 30, v6
	v_mul_f32_e32 v10, v134, v102
	v_fmac_f32_e32 v10, v136, v104
	v_fmac_f32_e32 v10, v138, v106
	v_fmac_f32_e32 v10, v140, v108
	v_fmac_f32_e32 v10, v142, v110
	v_fmac_f32_e32 v10, v144, v112
	v_fmac_f32_e32 v10, v146, v114
	v_fmac_f32_e32 v10, v149, v117
	v_cndmask_b32_e64 v9, 0, -1.0, s[8:9]
	v_fmac_f32_e32 v9, v135, v103
	v_fmac_f32_e32 v9, v137, v105
	v_fmac_f32_e32 v9, v139, v107
	v_fmac_f32_e32 v9, v141, v109
	v_fmac_f32_e32 v9, v143, v111
	v_fmac_f32_e32 v9, v145, v113
	v_fmac_f32_e32 v9, v148, v116
	v_add_f32_e32 v9, v9, v10
	v_add_f32_dpp v8, v7, v7 quad_perm:[1,0,3,2] row_mask:0xf bank_mask:0xf
	v_cndmask_b32_e64 v115, v115, v8, s[100:101]
	v_cvt_pk_bf16_f32 v8, v8, v8
	ds_write_b16 v5, v8 offset:4176
	v_fma_f32 v7, -v147, v115, -v9
	ds_read_b128 v[134:137], v4 offset:8448
	ds_read_b128 v[138:141], v4 offset:8480
	ds_read_b128 v[142:145], v4 offset:8512
	ds_read_b128 v[146:149], v4 offset:8544
	ds_read_b128 v[150:153], v4 offset:8576
	s_waitcnt lgkmcnt(11)
; #define LAS __attribute__((address_space(3)))
; __device__ __forceinline__ unsigned f2bf(float f) { unsigned u = __builtin_bit_cast(unsigned, f); return (u + 0x7fffu + ((u >> 16) & 1u)) >> 16; }
; __device__ __forceinline__ void gdn_prep_unit(Frame& F, int chain, int ci, unsigned char* rec, float* EGp, unsigned* qctr) {
;     ...
;         for (int c = 0; c < 64; ++c) {
;             float a0 = 0.f, a1 = 0.f, a2 = 0.f, a3 = 0.f;
; #pragma unroll
;             for (int k = 0; k < ((c + 3) / 4 + 1) / 2; ++k) { const f32x4 l4 = *(const LAS f32x4*)(Lrow + c * 256 + k * 32);
;                 a0 += l4.x * Tm[k][0]; a1 += l4.y * Tm[k][1]; a2 += l4.z * Tm[k][2]; a3 += l4.w * Tm[k][3]; }
;             float a = (a0 + a1) + (a2 + a3);
;             a += __builtin_bit_cast(float, __builtin_amdgcn_update_dpp(0, __builtin_bit_cast(int, a), 0xB1, 0xF, 0xF, false));
;             const float tn = ((c == j) ? 1.f : 0.f) - a;
;             Tm[c >> 3][c & 3] = (((c >> 2) & 1) == hh2) ? tn : Tm[c >> 3][c & 3];
;             if (hh2 == 0) *(LAS bf16*)(L + PL_TT + c * 144 + j * 2) = (bf16)f2bf(tn);
;         }
	v_cmp_eq_u32_e64 s[8:9], 31, v6
	v_mul_f32_e32 v12, v202, v102
	v_fmac_f32_e32 v12, v204, v104
	v_fmac_f32_e32 v12, v206, v106
	v_fmac_f32_e32 v12, v208, v108
	v_fmac_f32_e32 v12, v210, v110
	v_fmac_f32_e32 v12, v212, v112
	v_fmac_f32_e32 v12, v220, v114
	v_fmac_f32_e32 v12, v223, v117
	v_cndmask_b32_e64 v11, 0, -1.0, s[8:9]
	v_fmac_f32_e32 v11, v203, v103
	v_fmac_f32_e32 v11, v205, v105
	v_fmac_f32_e32 v11, v207, v107
	v_fmac_f32_e32 v11, v209, v109
	v_fmac_f32_e32 v11, v211, v111
	v_fmac_f32_e32 v11, v213, v113
	v_fmac_f32_e32 v11, v221, v115
	v_add_f32_e32 v11, v11, v12
	v_add_f32_dpp v8, v7, v7 quad_perm:[1,0,3,2] row_mask:0xf bank_mask:0xf
	v_cndmask_b32_e64 v116, v116, v8, s[100:101]
	v_cvt_pk_bf16_f32 v8, v8, v8
	ds_write_b16 v5, v8 offset:4320
	v_fma_f32 v7, -v222, v116, -v11
	ds_read_b128 v[202:205], v4 offset:8704
	ds_read_b128 v[206:209], v4 offset:8736
	ds_read_b128 v[210:213], v4 offset:8768
	ds_read_b128 v[220:223], v4 offset:8800
	ds_read_b128 v[224:227], v4 offset:8832
	s_waitcnt lgkmcnt(12)
	v_cmp_eq_u32_e64 s[8:9], 32, v6
	v_mul_f32_e32 v10, v166, v102
	v_fmac_f32_e32 v10, v168, v104
	v_fmac_f32_e32 v10, v170, v106
	v_fmac_f32_e32 v10, v172, v108
	v_fmac_f32_e32 v10, v174, v110
	v_fmac_f32_e32 v10, v176, v112
	v_fmac_f32_e32 v10, v178, v114
	v_fmac_f32_e32 v10, v180, v116
	v_cndmask_b32_e64 v9, 0, -1.0, s[8:9]
	v_fmac_f32_e32 v9, v167, v103
	v_fmac_f32_e32 v9, v169, v105
	v_fmac_f32_e32 v9, v171, v107
	v_fmac_f32_e32 v9, v173, v109
	v_fmac_f32_e32 v9, v175, v111
	v_fmac_f32_e32 v9, v177, v113
	v_fmac_f32_e32 v9, v179, v115
	v_add_f32_e32 v9, v9, v10
	v_add_f32_dpp v8, v7, v7 quad_perm:[1,0,3,2] row_mask:0xf bank_mask:0xf
	v_cndmask_b32_e64 v117, v117, v8, s[100:101]
	v_cvt_pk_bf16_f32 v8, v8, v8
	ds_write_b16 v5, v8 offset:4464
	v_fma_f32 v7, -v181, v117, -v9
	ds_read_b128 v[166:169], v4 offset:8960
	ds_read_b128 v[170:173], v4 offset:8992
	ds_read_b128 v[174:177], v4 offset:9024
	ds_read_b128 v[178:181], v4 offset:9056
	ds_read_b128 v[182:185], v4 offset:9088
	s_waitcnt lgkmcnt(12)
	v_cmp_eq_u32_e64 s[8:9], 33, v6
	v_mul_f32_e32 v12, v134, v102
	v_fmac_f32_e32 v12, v136, v104
	v_fmac_f32_e32 v12, v138, v106
	v_fmac_f32_e32 v12, v140, v108
	v_fmac_f32_e32 v12, v142, v110
	v_fmac_f32_e32 v12, v144, v112
	v_fmac_f32_e32 v12, v146, v114
	v_fmac_f32_e32 v12, v148, v116
	v_fmac_f32_e32 v12, v151, v119
	v_fmac_f32_e32 v12, v153, v121
	v_cndmask_b32_e64 v11, 0, -1.0, s[8:9]
	v_fmac_f32_e32 v11, v135, v103
	v_fmac_f32_e32 v11, v137, v105
	v_fmac_f32_e32 v11, v139, v107
	v_fmac_f32_e32 v11, v141, v109
	v_fmac_f32_e32 v11, v143, v111
	v_fmac_f32_e32 v11, v145, v113
	v_fmac_f32_e32 v11, v147, v115
	v_fmac_f32_e32 v11, v149, v117
	v_fmac_f32_e32 v11, v152, v120
	v_add_f32_e32 v11, v11, v12
	v_add_f32_dpp v8, v7, v7 quad_perm:[1,0,3,2] row_mask:0xf bank_mask:0xf
	v_cndmask_b32_e64 v118, v118, v8, s[98:99]
	v_cvt_pk_bf16_f32 v8, v8, v8
	ds_write_b16 v5, v8 offset:4608
	v_fma_f32 v7, -v150, v118, -v11
	ds_read_b128 v[134:137], v4 offset:9216
	ds_read_b128 v[138:141], v4 offset:9248
	ds_read_b128 v[142:145], v4 offset:9280
	ds_read_b128 v[146:149], v4 offset:9312
	ds_read_b128 v[150:153], v4 offset:9344
	s_waitcnt lgkmcnt(12)
	v_cmp_eq_u32_e64 s[8:9], 34, v6
	v_mul_f32_e32 v10, v202, v102
	v_fmac_f32_e32 v10, v204, v104
	v_fmac_f32_e32 v10, v206, v106
	v_fmac_f32_e32 v10, v208, v108
	v_fmac_f32_e32 v10, v210, v110
	v_fmac_f32_e32 v10, v212, v112
	v_fmac_f32_e32 v10, v220, v114
	v_fmac_f32_e32 v10, v222, v116
	v_fmac_f32_e32 v10, v224, v118
	v_fmac_f32_e32 v10, v227, v121
	v_cndmask_b32_e64 v9, 0, -1.0, s[8:9]
	v_fmac_f32_e32 v9, v203, v103
	v_fmac_f32_e32 v9, v205, v105
	v_fmac_f32_e32 v9, v207, v107
	v_fmac_f32_e32 v9, v209, v109
	v_fmac_f32_e32 v9, v211, v111
	v_fmac_f32_e32 v9, v213, v113
	v_fmac_f32_e32 v9, v221, v115
	v_fmac_f32_e32 v9, v223, v117
	v_fmac_f32_e32 v9, v226, v120
	v_add_f32_e32 v9, v9, v10
	v_add_f32_dpp v8, v7, v7 quad_perm:[1,0,3,2] row_mask:0xf bank_mask:0xf
	v_cndmask_b32_e64 v119, v119, v8, s[98:99]
	v_cvt_pk_bf16_f32 v8, v8, v8
	ds_write_b16 v5, v8 offset:4752
	v_fma_f32 v7, -v225, v119, -v9
	ds_read_b128 v[202:205], v4 offset:9472
	ds_read_b128 v[206:209], v4 offset:9504
	ds_read_b128 v[210:213], v4 offset:9536
	ds_read_b128 v[220:223], v4 offset:9568
	ds_read_b128 v[224:227], v4 offset:9600
	s_waitcnt lgkmcnt(12)
	v_cmp_eq_u32_e64 s[8:9], 35, v6
	v_mul_f32_e32 v12, v166, v102
	v_fmac_f32_e32 v12, v168, v104
	v_fmac_f32_e32 v12, v170, v106
	v_fmac_f32_e32 v12, v172, v108
	v_fmac_f32_e32 v12, v174, v110
	v_fmac_f32_e32 v12, v176, v112
	v_fmac_f32_e32 v12, v178, v114
	v_fmac_f32_e32 v12, v180, v116
	v_fmac_f32_e32 v12, v182, v118
	v_fmac_f32_e32 v12, v185, v121
	v_cndmask_b32_e64 v11, 0, -1.0, s[8:9]
	v_fmac_f32_e32 v11, v167, v103
	v_fmac_f32_e32 v11, v169, v105
	v_fmac_f32_e32 v11, v171, v107
	v_fmac_f32_e32 v11, v173, v109
	v_fmac_f32_e32 v11, v175, v111
	v_fmac_f32_e32 v11, v177, v113
	v_fmac_f32_e32 v11, v179, v115
	v_fmac_f32_e32 v11, v181, v117
	v_fmac_f32_e32 v11, v183, v119
	v_add_f32_e32 v11, v11, v12
	v_add_f32_dpp v8, v7, v7 quad_perm:[1,0,3,2] row_mask:0xf bank_mask:0xf
	v_cndmask_b32_e64 v120, v120, v8, s[98:99]
	v_cvt_pk_bf16_f32 v8, v8, v8
	ds_write_b16 v5, v8 offset:4896
	v_fma_f32 v7, -v184, v120, -v11
	ds_read_b128 v[166:169], v4 offset:9728
	ds_read_b128 v[170:173], v4 offset:9760
	ds_read_b128 v[174:177], v4 offset:9792
	ds_read_b128 v[178:181], v4 offset:9824
	ds_read_b128 v[182:185], v4 offset:9856
	s_waitcnt lgkmcnt(12)
; #define LAS __attribute__((address_space(3)))
; __device__ __forceinline__ unsigned f2bf(float f) { unsigned u = __builtin_bit_cast(unsigned, f); return (u + 0x7fffu + ((u >> 16) & 1u)) >> 16; }
; __device__ __forceinline__ void gdn_prep_unit(Frame& F, int chain, int ci, unsigned char* rec, float* EGp, unsigned* qctr) {
;     ...
;         for (int c = 0; c < 64; ++c) {
;             float a0 = 0.f, a1 = 0.f, a2 = 0.f, a3 = 0.f;
; #pragma unroll
;             for (int k = 0; k < ((c + 3) / 4 + 1) / 2; ++k) { const f32x4 l4 = *(const LAS f32x4*)(Lrow + c * 256 + k * 32);
;                 a0 += l4.x * Tm[k][0]; a1 += l4.y * Tm[k][1]; a2 += l4.z * Tm[k][2]; a3 += l4.w * Tm[k][3]; }
;             float a = (a0 + a1) + (a2 + a3);
;             a += __builtin_bit_cast(float, __builtin_amdgcn_update_dpp(0, __builtin_bit_cast(int, a), 0xB1, 0xF, 0xF, false));
;             const float tn = ((c == j) ? 1.f : 0.f) - a;
;             Tm[c >> 3][c & 3] = (((c >> 2) & 1) == hh2) ? tn : Tm[c >> 3][c & 3];
;             if (hh2 == 0) *(LAS bf16*)(L + PL_TT + c * 144 + j * 2) = (bf16)f2bf(tn);
;         }
	v_cmp_eq_u32_e64 s[8:9], 36, v6
	v_mul_f32_e32 v10, v134, v102
	v_fmac_f32_e32 v10, v136, v104
	v_fmac_f32_e32 v10, v138, v106
	v_fmac_f32_e32 v10, v140, v108
	v_fmac_f32_e32 v10, v142, v110
	v_fmac_f32_e32 v10, v144, v112
	v_fmac_f32_e32 v10, v146, v114
	v_fmac_f32_e32 v10, v148, v116
	v_fmac_f32_e32 v10, v150, v118
	v_fmac_f32_e32 v10, v152, v120
	v_cndmask_b32_e64 v9, 0, -1.0, s[8:9]
	v_fmac_f32_e32 v9, v135, v103
	v_fmac_f32_e32 v9, v137, v105
	v_fmac_f32_e32 v9, v139, v107
	v_fmac_f32_e32 v9, v141, v109
	v_fmac_f32_e32 v9, v143, v111
	v_fmac_f32_e32 v9, v145, v113
	v_fmac_f32_e32 v9, v147, v115
	v_fmac_f32_e32 v9, v149, v117
	v_fmac_f32_e32 v9, v151, v119
	v_add_f32_e32 v9, v9, v10
	v_add_f32_dpp v8, v7, v7 quad_perm:[1,0,3,2] row_mask:0xf bank_mask:0xf
	v_cndmask_b32_e64 v121, v121, v8, s[98:99]
	v_cvt_pk_bf16_f32 v8, v8, v8
	ds_write_b16 v5, v8 offset:5040
	v_fma_f32 v7, -v153, v121, -v9
	ds_read_b128 v[134:137], v4 offset:9984
	ds_read_b128 v[138:141], v4 offset:10016
	ds_read_b128 v[142:145], v4 offset:10048
	ds_read_b128 v[146:149], v4 offset:10080
	ds_read_b128 v[150:153], v4 offset:10112
	s_waitcnt lgkmcnt(12)
	v_cmp_eq_u32_e64 s[8:9], 37, v6
	v_mul_f32_e32 v12, v202, v102
	v_fmac_f32_e32 v12, v204, v104
	v_fmac_f32_e32 v12, v206, v106
	v_fmac_f32_e32 v12, v208, v108
	v_fmac_f32_e32 v12, v210, v110
	v_fmac_f32_e32 v12, v212, v112
	v_fmac_f32_e32 v12, v220, v114
	v_fmac_f32_e32 v12, v222, v116
	v_fmac_f32_e32 v12, v225, v119
	v_fmac_f32_e32 v12, v227, v121
	v_cndmask_b32_e64 v11, 0, -1.0, s[8:9]
	v_fmac_f32_e32 v11, v203, v103
	v_fmac_f32_e32 v11, v205, v105
	v_fmac_f32_e32 v11, v207, v107
	v_fmac_f32_e32 v11, v209, v109
	v_fmac_f32_e32 v11, v211, v111
	v_fmac_f32_e32 v11, v213, v113
	v_fmac_f32_e32 v11, v221, v115
	v_fmac_f32_e32 v11, v223, v117
	v_fmac_f32_e32 v11, v226, v120
	v_add_f32_e32 v11, v11, v12
	v_add_f32_dpp v8, v7, v7 quad_perm:[1,0,3,2] row_mask:0xf bank_mask:0xf
	v_cndmask_b32_e64 v118, v118, v8, s[100:101]
	v_cvt_pk_bf16_f32 v8, v8, v8
	ds_write_b16 v5, v8 offset:5184
	v_fma_f32 v7, -v224, v118, -v11
	ds_read_b128 v[202:205], v4 offset:10240
	ds_read_b128 v[206:209], v4 offset:10272
	ds_read_b128 v[210:213], v4 offset:10304
	ds_read_b128 v[220:223], v4 offset:10336
	ds_read_b128 v[224:227], v4 offset:10368
	s_waitcnt lgkmcnt(12)
	v_cmp_eq_u32_e64 s[8:9], 38, v6
	v_mul_f32_e32 v10, v166, v102
	v_fmac_f32_e32 v10, v168, v104
	v_fmac_f32_e32 v10, v170, v106
	v_fmac_f32_e32 v10, v172, v108
	v_fmac_f32_e32 v10, v174, v110
	v_fmac_f32_e32 v10, v176, v112
	v_fmac_f32_e32 v10, v178, v114
	v_fmac_f32_e32 v10, v180, v116
	v_fmac_f32_e32 v10, v182, v118
	v_fmac_f32_e32 v10, v185, v121
	v_cndmask_b32_e64 v9, 0, -1.0, s[8:9]
	v_fmac_f32_e32 v9, v167, v103
	v_fmac_f32_e32 v9, v169, v105
	v_fmac_f32_e32 v9, v171, v107
	v_fmac_f32_e32 v9, v173, v109
	v_fmac_f32_e32 v9, v175, v111
	v_fmac_f32_e32 v9, v177, v113
	v_fmac_f32_e32 v9, v179, v115
	v_fmac_f32_e32 v9, v181, v117
	v_fmac_f32_e32 v9, v184, v120
	v_add_f32_e32 v9, v9, v10
	v_add_f32_dpp v8, v7, v7 quad_perm:[1,0,3,2] row_mask:0xf bank_mask:0xf
	v_cndmask_b32_e64 v119, v119, v8, s[100:101]
	v_cvt_pk_bf16_f32 v8, v8, v8
	ds_write_b16 v5, v8 offset:5328
	v_fma_f32 v7, -v183, v119, -v9
	ds_read_b128 v[166:169], v4 offset:10496
	ds_read_b128 v[170:173], v4 offset:10528
	ds_read_b128 v[174:177], v4 offset:10560
	ds_read_b128 v[178:181], v4 offset:10592
	ds_read_b128 v[182:185], v4 offset:10624
	ds_read_b128 v[186:189], v4 offset:10656
	s_waitcnt lgkmcnt(13)
	v_cmp_eq_u32_e64 s[8:9], 39, v6
	v_mul_f32_e32 v12, v134, v102
	v_fmac_f32_e32 v12, v136, v104
	v_fmac_f32_e32 v12, v138, v106
	v_fmac_f32_e32 v12, v140, v108
	v_fmac_f32_e32 v12, v142, v110
	v_fmac_f32_e32 v12, v144, v112
	v_fmac_f32_e32 v12, v146, v114
	v_fmac_f32_e32 v12, v148, v116
	v_fmac_f32_e32 v12, v150, v118
	v_fmac_f32_e32 v12, v153, v121
	v_cndmask_b32_e64 v11, 0, -1.0, s[8:9]
	v_fmac_f32_e32 v11, v135, v103
	v_fmac_f32_e32 v11, v137, v105
	v_fmac_f32_e32 v11, v139, v107
	v_fmac_f32_e32 v11, v141, v109
	v_fmac_f32_e32 v11, v143, v111
	v_fmac_f32_e32 v11, v145, v113
	v_fmac_f32_e32 v11, v147, v115
	v_fmac_f32_e32 v11, v149, v117
	v_fmac_f32_e32 v11, v151, v119
	v_add_f32_e32 v11, v11, v12
	v_add_f32_dpp v8, v7, v7 quad_perm:[1,0,3,2] row_mask:0xf bank_mask:0xf
	v_cndmask_b32_e64 v120, v120, v8, s[100:101]
	v_cvt_pk_bf16_f32 v8, v8, v8
	ds_write_b16 v5, v8 offset:5472
	v_fma_f32 v7, -v152, v120, -v11
	ds_read_b128 v[134:137], v4 offset:10752
	ds_read_b128 v[138:141], v4 offset:10784
	ds_read_b128 v[142:145], v4 offset:10816
	ds_read_b128 v[146:149], v4 offset:10848
	ds_read_b128 v[150:153], v4 offset:10880
	ds_read_b128 v[154:157], v4 offset:10912
	s_waitcnt lgkmcnt(14)
	v_cmp_eq_u32_e64 s[8:9], 40, v6
	v_mul_f32_e32 v10, v202, v102
	v_fmac_f32_e32 v10, v204, v104
	v_fmac_f32_e32 v10, v206, v106
	v_fmac_f32_e32 v10, v208, v108
	v_fmac_f32_e32 v10, v210, v110
	v_fmac_f32_e32 v10, v212, v112
	v_fmac_f32_e32 v10, v220, v114
	v_fmac_f32_e32 v10, v222, v116
	v_fmac_f32_e32 v10, v224, v118
	v_fmac_f32_e32 v10, v226, v120
	v_cndmask_b32_e64 v9, 0, -1.0, s[8:9]
	v_fmac_f32_e32 v9, v203, v103
	v_fmac_f32_e32 v9, v205, v105
	v_fmac_f32_e32 v9, v207, v107
	v_fmac_f32_e32 v9, v209, v109
	v_fmac_f32_e32 v9, v211, v111
	v_fmac_f32_e32 v9, v213, v113
	v_fmac_f32_e32 v9, v221, v115
	v_fmac_f32_e32 v9, v223, v117
	v_fmac_f32_e32 v9, v225, v119
	v_add_f32_e32 v9, v9, v10
	v_add_f32_dpp v8, v7, v7 quad_perm:[1,0,3,2] row_mask:0xf bank_mask:0xf
	v_cndmask_b32_e64 v121, v121, v8, s[100:101]
	v_cvt_pk_bf16_f32 v8, v8, v8
	ds_write_b16 v5, v8 offset:5616
	v_fma_f32 v7, -v227, v121, -v9
	ds_read_b128 v[202:205], v4 offset:11008
	ds_read_b128 v[206:209], v4 offset:11040
	ds_read_b128 v[210:213], v4 offset:11072
	ds_read_b128 v[220:223], v4 offset:11104
	ds_read_b128 v[224:227], v4 offset:11136
	ds_read_b128 v[228:231], v4 offset:11168
	s_waitcnt lgkmcnt(14)
; #define LAS __attribute__((address_space(3)))
; __device__ __forceinline__ unsigned f2bf(float f) { unsigned u = __builtin_bit_cast(unsigned, f); return (u + 0x7fffu + ((u >> 16) & 1u)) >> 16; }
; __device__ __forceinline__ void gdn_prep_unit(Frame& F, int chain, int ci, unsigned char* rec, float* EGp, unsigned* qctr) {
;     ...
;         for (int c = 0; c < 64; ++c) {
;             float a0 = 0.f, a1 = 0.f, a2 = 0.f, a3 = 0.f;
; #pragma unroll
;             for (int k = 0; k < ((c + 3) / 4 + 1) / 2; ++k) { const f32x4 l4 = *(const LAS f32x4*)(Lrow + c * 256 + k * 32);
;                 a0 += l4.x * Tm[k][0]; a1 += l4.y * Tm[k][1]; a2 += l4.z * Tm[k][2]; a3 += l4.w * Tm[k][3]; }
;             float a = (a0 + a1) + (a2 + a3);
;             a += __builtin_bit_cast(float, __builtin_amdgcn_update_dpp(0, __builtin_bit_cast(int, a), 0xB1, 0xF, 0xF, false));
;             const float tn = ((c == j) ? 1.f : 0.f) - a;
;             Tm[c >> 3][c & 3] = (((c >> 2) & 1) == hh2) ? tn : Tm[c >> 3][c & 3];
;             if (hh2 == 0) *(LAS bf16*)(L + PL_TT + c * 144 + j * 2) = (bf16)f2bf(tn);
;         }
	v_cmp_eq_u32_e64 s[8:9], 41, v6
	v_mul_f32_e32 v12, v166, v102
	v_fmac_f32_e32 v12, v168, v104
	v_fmac_f32_e32 v12, v170, v106
	v_fmac_f32_e32 v12, v172, v108
	v_fmac_f32_e32 v12, v174, v110
	v_fmac_f32_e32 v12, v176, v112
	v_fmac_f32_e32 v12, v178, v114
	v_fmac_f32_e32 v12, v180, v116
	v_fmac_f32_e32 v12, v182, v118
	v_fmac_f32_e32 v12, v184, v120
	v_fmac_f32_e32 v12, v187, v123
	v_fmac_f32_e32 v12, v189, v125
	v_cndmask_b32_e64 v11, 0, -1.0, s[8:9]
	v_fmac_f32_e32 v11, v167, v103
	v_fmac_f32_e32 v11, v169, v105
	v_fmac_f32_e32 v11, v171, v107
	v_fmac_f32_e32 v11, v173, v109
	v_fmac_f32_e32 v11, v175, v111
	v_fmac_f32_e32 v11, v177, v113
	v_fmac_f32_e32 v11, v179, v115
	v_fmac_f32_e32 v11, v181, v117
	v_fmac_f32_e32 v11, v183, v119
	v_fmac_f32_e32 v11, v185, v121
	v_fmac_f32_e32 v11, v188, v124
	v_add_f32_e32 v11, v11, v12
	v_add_f32_dpp v8, v7, v7 quad_perm:[1,0,3,2] row_mask:0xf bank_mask:0xf
	v_cndmask_b32_e64 v122, v122, v8, s[98:99]
	v_cvt_pk_bf16_f32 v8, v8, v8
	ds_write_b16 v5, v8 offset:5760
	v_fma_f32 v7, -v186, v122, -v11
	ds_read_b128 v[166:169], v4 offset:11264
	ds_read_b128 v[170:173], v4 offset:11296
	ds_read_b128 v[174:177], v4 offset:11328
	ds_read_b128 v[178:181], v4 offset:11360
	ds_read_b128 v[182:185], v4 offset:11392
	ds_read_b128 v[186:189], v4 offset:11424
	s_waitcnt lgkmcnt(14)
	v_cmp_eq_u32_e64 s[8:9], 42, v6
	v_mul_f32_e32 v10, v134, v102
	v_fmac_f32_e32 v10, v136, v104
	v_fmac_f32_e32 v10, v138, v106
	v_fmac_f32_e32 v10, v140, v108
	v_fmac_f32_e32 v10, v142, v110
	v_fmac_f32_e32 v10, v144, v112
	v_fmac_f32_e32 v10, v146, v114
	v_fmac_f32_e32 v10, v148, v116
	v_fmac_f32_e32 v10, v150, v118
	v_fmac_f32_e32 v10, v152, v120
	v_fmac_f32_e32 v10, v154, v122
	v_fmac_f32_e32 v10, v157, v125
	v_cndmask_b32_e64 v9, 0, -1.0, s[8:9]
	v_fmac_f32_e32 v9, v135, v103
	v_fmac_f32_e32 v9, v137, v105
	v_fmac_f32_e32 v9, v139, v107
	v_fmac_f32_e32 v9, v141, v109
	v_fmac_f32_e32 v9, v143, v111
	v_fmac_f32_e32 v9, v145, v113
	v_fmac_f32_e32 v9, v147, v115
	v_fmac_f32_e32 v9, v149, v117
	v_fmac_f32_e32 v9, v151, v119
	v_fmac_f32_e32 v9, v153, v121
	v_fmac_f32_e32 v9, v156, v124
	v_add_f32_e32 v9, v9, v10
	v_add_f32_dpp v8, v7, v7 quad_perm:[1,0,3,2] row_mask:0xf bank_mask:0xf
	v_cndmask_b32_e64 v123, v123, v8, s[98:99]
	v_cvt_pk_bf16_f32 v8, v8, v8
	ds_write_b16 v5, v8 offset:5904
	v_fma_f32 v7, -v155, v123, -v9
	ds_read_b128 v[134:137], v4 offset:11520
	ds_read_b128 v[138:141], v4 offset:11552
	ds_read_b128 v[142:145], v4 offset:11584
	ds_read_b128 v[146:149], v4 offset:11616
	ds_read_b128 v[150:153], v4 offset:11648
	ds_read_b128 v[154:157], v4 offset:11680
	s_waitcnt lgkmcnt(14)
	v_cmp_eq_u32_e64 s[8:9], 43, v6
	v_mul_f32_e32 v12, v202, v102
	v_fmac_f32_e32 v12, v204, v104
	v_fmac_f32_e32 v12, v206, v106
	v_fmac_f32_e32 v12, v208, v108
	v_fmac_f32_e32 v12, v210, v110
	v_fmac_f32_e32 v12, v212, v112
	v_fmac_f32_e32 v12, v220, v114
	v_fmac_f32_e32 v12, v222, v116
	v_fmac_f32_e32 v12, v224, v118
	v_fmac_f32_e32 v12, v226, v120
	v_fmac_f32_e32 v12, v228, v122
	v_fmac_f32_e32 v12, v231, v125
	v_cndmask_b32_e64 v11, 0, -1.0, s[8:9]
	v_fmac_f32_e32 v11, v203, v103
	v_fmac_f32_e32 v11, v205, v105
	v_fmac_f32_e32 v11, v207, v107
	v_fmac_f32_e32 v11, v209, v109
	v_fmac_f32_e32 v11, v211, v111
	v_fmac_f32_e32 v11, v213, v113
	v_fmac_f32_e32 v11, v221, v115
	v_fmac_f32_e32 v11, v223, v117
	v_fmac_f32_e32 v11, v225, v119
	v_fmac_f32_e32 v11, v227, v121
	v_fmac_f32_e32 v11, v229, v123
	v_add_f32_e32 v11, v11, v12
	v_add_f32_dpp v8, v7, v7 quad_perm:[1,0,3,2] row_mask:0xf bank_mask:0xf
	v_cndmask_b32_e64 v124, v124, v8, s[98:99]
	v_cvt_pk_bf16_f32 v8, v8, v8
	ds_write_b16 v5, v8 offset:6048
	v_fma_f32 v7, -v230, v124, -v11
	ds_read_b128 v[202:205], v4 offset:11776
	ds_read_b128 v[206:209], v4 offset:11808
	ds_read_b128 v[210:213], v4 offset:11840
	ds_read_b128 v[220:223], v4 offset:11872
	ds_read_b128 v[224:227], v4 offset:11904
	ds_read_b128 v[228:231], v4 offset:11936
	s_waitcnt lgkmcnt(14)
	v_cmp_eq_u32_e64 s[8:9], 44, v6
	v_mul_f32_e32 v10, v166, v102
	v_fmac_f32_e32 v10, v168, v104
	v_fmac_f32_e32 v10, v170, v106
	v_fmac_f32_e32 v10, v172, v108
	v_fmac_f32_e32 v10, v174, v110
	v_fmac_f32_e32 v10, v176, v112
	v_fmac_f32_e32 v10, v178, v114
	v_fmac_f32_e32 v10, v180, v116
	v_fmac_f32_e32 v10, v182, v118
	v_fmac_f32_e32 v10, v184, v120
	v_fmac_f32_e32 v10, v186, v122
	v_fmac_f32_e32 v10, v188, v124
	v_cndmask_b32_e64 v9, 0, -1.0, s[8:9]
	v_fmac_f32_e32 v9, v167, v103
	v_fmac_f32_e32 v9, v169, v105
	v_fmac_f32_e32 v9, v171, v107
	v_fmac_f32_e32 v9, v173, v109
	v_fmac_f32_e32 v9, v175, v111
	v_fmac_f32_e32 v9, v177, v113
	v_fmac_f32_e32 v9, v179, v115
	v_fmac_f32_e32 v9, v181, v117
	v_fmac_f32_e32 v9, v183, v119
	v_fmac_f32_e32 v9, v185, v121
	v_fmac_f32_e32 v9, v187, v123
	v_add_f32_e32 v9, v9, v10
	v_add_f32_dpp v8, v7, v7 quad_perm:[1,0,3,2] row_mask:0xf bank_mask:0xf
	v_cndmask_b32_e64 v125, v125, v8, s[98:99]
	v_cvt_pk_bf16_f32 v8, v8, v8
	ds_write_b16 v5, v8 offset:6192
	v_fma_f32 v7, -v189, v125, -v9
	ds_read_b128 v[166:169], v4 offset:12032
	ds_read_b128 v[170:173], v4 offset:12064
	ds_read_b128 v[174:177], v4 offset:12096
	ds_read_b128 v[178:181], v4 offset:12128
	ds_read_b128 v[182:185], v4 offset:12160
	ds_read_b128 v[186:189], v4 offset:12192
	s_waitcnt lgkmcnt(14)
; #define LAS __attribute__((address_space(3)))
; __device__ __forceinline__ unsigned f2bf(float f) { unsigned u = __builtin_bit_cast(unsigned, f); return (u + 0x7fffu + ((u >> 16) & 1u)) >> 16; }
; __device__ __forceinline__ void gdn_prep_unit(Frame& F, int chain, int ci, unsigned char* rec, float* EGp, unsigned* qctr) {
;     ...
;         for (int c = 0; c < 64; ++c) {
;             float a0 = 0.f, a1 = 0.f, a2 = 0.f, a3 = 0.f;
; #pragma unroll
;             for (int k = 0; k < ((c + 3) / 4 + 1) / 2; ++k) { const f32x4 l4 = *(const LAS f32x4*)(Lrow + c * 256 + k * 32);
;                 a0 += l4.x * Tm[k][0]; a1 += l4.y * Tm[k][1]; a2 += l4.z * Tm[k][2]; a3 += l4.w * Tm[k][3]; }
;             float a = (a0 + a1) + (a2 + a3);
;             a += __builtin_bit_cast(float, __builtin_amdgcn_update_dpp(0, __builtin_bit_cast(int, a), 0xB1, 0xF, 0xF, false));
;             const float tn = ((c == j) ? 1.f : 0.f) - a;
;             Tm[c >> 3][c & 3] = (((c >> 2) & 1) == hh2) ? tn : Tm[c >> 3][c & 3];
;             if (hh2 == 0) *(LAS bf16*)(L + PL_TT + c * 144 + j * 2) = (bf16)f2bf(tn);
;         }
	v_cmp_eq_u32_e64 s[8:9], 45, v6
	v_mul_f32_e32 v12, v134, v102
	v_fmac_f32_e32 v12, v136, v104
	v_fmac_f32_e32 v12, v138, v106
	v_fmac_f32_e32 v12, v140, v108
	v_fmac_f32_e32 v12, v142, v110
	v_fmac_f32_e32 v12, v144, v112
	v_fmac_f32_e32 v12, v146, v114
	v_fmac_f32_e32 v12, v148, v116
	v_fmac_f32_e32 v12, v150, v118
	v_fmac_f32_e32 v12, v152, v120
	v_fmac_f32_e32 v12, v155, v123
	v_fmac_f32_e32 v12, v157, v125
	v_cndmask_b32_e64 v11, 0, -1.0, s[8:9]
	v_fmac_f32_e32 v11, v135, v103
	v_fmac_f32_e32 v11, v137, v105
	v_fmac_f32_e32 v11, v139, v107
	v_fmac_f32_e32 v11, v141, v109
	v_fmac_f32_e32 v11, v143, v111
	v_fmac_f32_e32 v11, v145, v113
	v_fmac_f32_e32 v11, v147, v115
	v_fmac_f32_e32 v11, v149, v117
	v_fmac_f32_e32 v11, v151, v119
	v_fmac_f32_e32 v11, v153, v121
	v_fmac_f32_e32 v11, v156, v124
	v_add_f32_e32 v11, v11, v12
	v_add_f32_dpp v8, v7, v7 quad_perm:[1,0,3,2] row_mask:0xf bank_mask:0xf
	v_cndmask_b32_e64 v122, v122, v8, s[100:101]
	v_cvt_pk_bf16_f32 v8, v8, v8
	ds_write_b16 v5, v8 offset:6336
	v_fma_f32 v7, -v154, v122, -v11
	ds_read_b128 v[134:137], v4 offset:12288
	ds_read_b128 v[138:141], v4 offset:12320
	ds_read_b128 v[142:145], v4 offset:12352
	ds_read_b128 v[146:149], v4 offset:12384
	ds_read_b128 v[150:153], v4 offset:12416
	ds_read_b128 v[154:157], v4 offset:12448
	s_waitcnt lgkmcnt(14)
	v_cmp_eq_u32_e64 s[8:9], 46, v6
	v_mul_f32_e32 v10, v202, v102
	v_fmac_f32_e32 v10, v204, v104
	v_fmac_f32_e32 v10, v206, v106
	v_fmac_f32_e32 v10, v208, v108
	v_fmac_f32_e32 v10, v210, v110
	v_fmac_f32_e32 v10, v212, v112
	v_fmac_f32_e32 v10, v220, v114
	v_fmac_f32_e32 v10, v222, v116
	v_fmac_f32_e32 v10, v224, v118
	v_fmac_f32_e32 v10, v226, v120
	v_fmac_f32_e32 v10, v228, v122
	v_fmac_f32_e32 v10, v231, v125
	v_cndmask_b32_e64 v9, 0, -1.0, s[8:9]
	v_fmac_f32_e32 v9, v203, v103
	v_fmac_f32_e32 v9, v205, v105
	v_fmac_f32_e32 v9, v207, v107
	v_fmac_f32_e32 v9, v209, v109
	v_fmac_f32_e32 v9, v211, v111
	v_fmac_f32_e32 v9, v213, v113
	v_fmac_f32_e32 v9, v221, v115
	v_fmac_f32_e32 v9, v223, v117
	v_fmac_f32_e32 v9, v225, v119
	v_fmac_f32_e32 v9, v227, v121
	v_fmac_f32_e32 v9, v230, v124
	v_add_f32_e32 v9, v9, v10
	v_add_f32_dpp v8, v7, v7 quad_perm:[1,0,3,2] row_mask:0xf bank_mask:0xf
	v_cndmask_b32_e64 v123, v123, v8, s[100:101]
	v_cvt_pk_bf16_f32 v8, v8, v8
	ds_write_b16 v5, v8 offset:6480
	v_fma_f32 v7, -v229, v123, -v9
	ds_read_b128 v[202:205], v4 offset:12544
	ds_read_b128 v[206:209], v4 offset:12576
	ds_read_b128 v[210:213], v4 offset:12608
	ds_read_b128 v[220:223], v4 offset:12640
	ds_read_b128 v[224:227], v4 offset:12672
	ds_read_b128 v[228:231], v4 offset:12704
	ds_read_b128 v[232:235], v4 offset:12736
	s_waitcnt lgkmcnt(15)
	v_cmp_eq_u32_e64 s[8:9], 47, v6
	v_mul_f32_e32 v12, v166, v102
	v_fmac_f32_e32 v12, v168, v104
	v_fmac_f32_e32 v12, v170, v106
	v_fmac_f32_e32 v12, v172, v108
	v_fmac_f32_e32 v12, v174, v110
	v_fmac_f32_e32 v12, v176, v112
	v_fmac_f32_e32 v12, v178, v114
	v_fmac_f32_e32 v12, v180, v116
	v_fmac_f32_e32 v12, v182, v118
	v_fmac_f32_e32 v12, v184, v120
	v_fmac_f32_e32 v12, v186, v122
	v_fmac_f32_e32 v12, v189, v125
	v_cndmask_b32_e64 v11, 0, -1.0, s[8:9]
	v_fmac_f32_e32 v11, v167, v103
	v_fmac_f32_e32 v11, v169, v105
	v_fmac_f32_e32 v11, v171, v107
	v_fmac_f32_e32 v11, v173, v109
	v_fmac_f32_e32 v11, v175, v111
	v_fmac_f32_e32 v11, v177, v113
	v_fmac_f32_e32 v11, v179, v115
	v_fmac_f32_e32 v11, v181, v117
	v_fmac_f32_e32 v11, v183, v119
	v_fmac_f32_e32 v11, v185, v121
	v_fmac_f32_e32 v11, v187, v123
	v_add_f32_e32 v11, v11, v12
	v_add_f32_dpp v8, v7, v7 quad_perm:[1,0,3,2] row_mask:0xf bank_mask:0xf
	v_cndmask_b32_e64 v124, v124, v8, s[100:101]
	v_cvt_pk_bf16_f32 v8, v8, v8
	ds_write_b16 v5, v8 offset:6624
	v_fma_f32 v7, -v188, v124, -v11
	ds_read_b128 v[166:169], v4 offset:12800
	ds_read_b128 v[170:173], v4 offset:12832
	ds_read_b128 v[174:177], v4 offset:12864
	ds_read_b128 v[178:181], v4 offset:12896
	ds_read_b128 v[182:185], v4 offset:12928
	ds_read_b128 v[186:189], v4 offset:12960
	ds_read_b128 v[190:193], v4 offset:12992
	s_waitcnt lgkmcnt(15)
	v_cmp_eq_u32_e64 s[8:9], 48, v6
	v_mul_f32_e32 v10, v134, v102
	v_fmac_f32_e32 v10, v136, v104
	v_fmac_f32_e32 v10, v138, v106
	v_fmac_f32_e32 v10, v140, v108
	v_fmac_f32_e32 v10, v142, v110
	v_fmac_f32_e32 v10, v144, v112
	v_fmac_f32_e32 v10, v146, v114
	v_fmac_f32_e32 v10, v148, v116
	v_fmac_f32_e32 v10, v150, v118
	v_fmac_f32_e32 v10, v152, v120
	v_fmac_f32_e32 v10, v154, v122
	v_fmac_f32_e32 v10, v156, v124
	v_cndmask_b32_e64 v9, 0, -1.0, s[8:9]
	v_fmac_f32_e32 v9, v135, v103
	v_fmac_f32_e32 v9, v137, v105
	v_fmac_f32_e32 v9, v139, v107
	v_fmac_f32_e32 v9, v141, v109
	v_fmac_f32_e32 v9, v143, v111
	v_fmac_f32_e32 v9, v145, v113
	v_fmac_f32_e32 v9, v147, v115
	v_fmac_f32_e32 v9, v149, v117
	v_fmac_f32_e32 v9, v151, v119
	v_fmac_f32_e32 v9, v153, v121
	v_fmac_f32_e32 v9, v155, v123
	v_add_f32_e32 v9, v9, v10
	v_add_f32_dpp v8, v7, v7 quad_perm:[1,0,3,2] row_mask:0xf bank_mask:0xf
	v_cndmask_b32_e64 v125, v125, v8, s[100:101]
	v_cvt_pk_bf16_f32 v8, v8, v8
	ds_write_b16 v5, v8 offset:6768
	v_fma_f32 v7, -v157, v125, -v9
	ds_read_b128 v[134:137], v4 offset:13056
	ds_read_b128 v[138:141], v4 offset:13088
	ds_read_b128 v[142:145], v4 offset:13120
	ds_read_b128 v[146:149], v4 offset:13152
	ds_read_b128 v[150:153], v4 offset:13184
	ds_read_b128 v[154:157], v4 offset:13216
	ds_read_b128 v[158:161], v4 offset:13248
	s_waitcnt lgkmcnt(15)
; #define LAS __attribute__((address_space(3)))
; __device__ __forceinline__ unsigned f2bf(float f) { unsigned u = __builtin_bit_cast(unsigned, f); return (u + 0x7fffu + ((u >> 16) & 1u)) >> 16; }
; __device__ __forceinline__ void gdn_prep_unit(Frame& F, int chain, int ci, unsigned char* rec, float* EGp, unsigned* qctr) {
;     ...
;         for (int c = 0; c < 64; ++c) {
;             float a0 = 0.f, a1 = 0.f, a2 = 0.f, a3 = 0.f;
; #pragma unroll
;             for (int k = 0; k < ((c + 3) / 4 + 1) / 2; ++k) { const f32x4 l4 = *(const LAS f32x4*)(Lrow + c * 256 + k * 32);
;                 a0 += l4.x * Tm[k][0]; a1 += l4.y * Tm[k][1]; a2 += l4.z * Tm[k][2]; a3 += l4.w * Tm[k][3]; }
;             float a = (a0 + a1) + (a2 + a3);
;             a += __builtin_bit_cast(float, __builtin_amdgcn_update_dpp(0, __builtin_bit_cast(int, a), 0xB1, 0xF, 0xF, false));
;             const float tn = ((c == j) ? 1.f : 0.f) - a;
;             Tm[c >> 3][c & 3] = (((c >> 2) & 1) == hh2) ? tn : Tm[c >> 3][c & 3];
;             if (hh2 == 0) *(LAS bf16*)(L + PL_TT + c * 144 + j * 2) = (bf16)f2bf(tn);
;         }
	v_cmp_eq_u32_e64 s[8:9], 49, v6
	v_mul_f32_e32 v12, v202, v102
	v_fmac_f32_e32 v12, v204, v104
	v_fmac_f32_e32 v12, v206, v106
	v_fmac_f32_e32 v12, v208, v108
	v_fmac_f32_e32 v12, v210, v110
	v_fmac_f32_e32 v12, v212, v112
	v_fmac_f32_e32 v12, v220, v114
	v_fmac_f32_e32 v12, v222, v116
	v_fmac_f32_e32 v12, v224, v118
	v_fmac_f32_e32 v12, v226, v120
	v_fmac_f32_e32 v12, v228, v122
	v_fmac_f32_e32 v12, v230, v124
	v_fmac_f32_e32 v12, v233, v127
	v_fmac_f32_e32 v12, v235, v129
	v_cndmask_b32_e64 v11, 0, -1.0, s[8:9]
	v_fmac_f32_e32 v11, v203, v103
	v_fmac_f32_e32 v11, v205, v105
	v_fmac_f32_e32 v11, v207, v107
	v_fmac_f32_e32 v11, v209, v109
	v_fmac_f32_e32 v11, v211, v111
	v_fmac_f32_e32 v11, v213, v113
	v_fmac_f32_e32 v11, v221, v115
	v_fmac_f32_e32 v11, v223, v117
	v_fmac_f32_e32 v11, v225, v119
	v_fmac_f32_e32 v11, v227, v121
	v_fmac_f32_e32 v11, v229, v123
	v_fmac_f32_e32 v11, v231, v125
	v_fmac_f32_e32 v11, v234, v128
	v_add_f32_e32 v11, v11, v12
	v_add_f32_dpp v8, v7, v7 quad_perm:[1,0,3,2] row_mask:0xf bank_mask:0xf
	v_cndmask_b32_e64 v126, v126, v8, s[98:99]
	v_cvt_pk_bf16_f32 v8, v8, v8
	ds_write_b16 v5, v8 offset:6912
	v_fma_f32 v7, -v232, v126, -v11
	ds_read_b128 v[202:205], v4 offset:13312
	ds_read_b128 v[206:209], v4 offset:13344
	ds_read_b128 v[210:213], v4 offset:13376
	ds_read_b128 v[220:223], v4 offset:13408
	ds_read_b128 v[224:227], v4 offset:13440
	ds_read_b128 v[228:231], v4 offset:13472
	ds_read_b128 v[232:235], v4 offset:13504
	s_waitcnt lgkmcnt(15)
	v_cmp_eq_u32_e64 s[8:9], 50, v6
	v_mul_f32_e32 v10, v166, v102
	v_fmac_f32_e32 v10, v168, v104
	v_fmac_f32_e32 v10, v170, v106
	v_fmac_f32_e32 v10, v172, v108
	v_fmac_f32_e32 v10, v174, v110
	v_fmac_f32_e32 v10, v176, v112
	v_fmac_f32_e32 v10, v178, v114
	v_fmac_f32_e32 v10, v180, v116
	v_fmac_f32_e32 v10, v182, v118
	v_fmac_f32_e32 v10, v184, v120
	v_fmac_f32_e32 v10, v186, v122
	v_fmac_f32_e32 v10, v188, v124
	v_fmac_f32_e32 v10, v190, v126
	v_fmac_f32_e32 v10, v193, v129
	v_cndmask_b32_e64 v9, 0, -1.0, s[8:9]
	v_fmac_f32_e32 v9, v167, v103
	v_fmac_f32_e32 v9, v169, v105
	v_fmac_f32_e32 v9, v171, v107
	v_fmac_f32_e32 v9, v173, v109
	v_fmac_f32_e32 v9, v175, v111
	v_fmac_f32_e32 v9, v177, v113
	v_fmac_f32_e32 v9, v179, v115
	v_fmac_f32_e32 v9, v181, v117
	v_fmac_f32_e32 v9, v183, v119
	v_fmac_f32_e32 v9, v185, v121
	v_fmac_f32_e32 v9, v187, v123
	v_fmac_f32_e32 v9, v189, v125
	v_fmac_f32_e32 v9, v192, v128
	v_add_f32_e32 v9, v9, v10
	v_add_f32_dpp v8, v7, v7 quad_perm:[1,0,3,2] row_mask:0xf bank_mask:0xf
	v_cndmask_b32_e64 v127, v127, v8, s[98:99]
	v_cvt_pk_bf16_f32 v8, v8, v8
	ds_write_b16 v5, v8 offset:7056
	v_fma_f32 v7, -v191, v127, -v9
	ds_read_b128 v[166:169], v4 offset:13568
	ds_read_b128 v[170:173], v4 offset:13600
	ds_read_b128 v[174:177], v4 offset:13632
	ds_read_b128 v[178:181], v4 offset:13664
	ds_read_b128 v[182:185], v4 offset:13696
	ds_read_b128 v[186:189], v4 offset:13728
	ds_read_b128 v[190:193], v4 offset:13760
	s_waitcnt lgkmcnt(15)
	v_cmp_eq_u32_e64 s[8:9], 51, v6
	v_mul_f32_e32 v12, v134, v102
	v_fmac_f32_e32 v12, v136, v104
	v_fmac_f32_e32 v12, v138, v106
	v_fmac_f32_e32 v12, v140, v108
	v_fmac_f32_e32 v12, v142, v110
	v_fmac_f32_e32 v12, v144, v112
	v_fmac_f32_e32 v12, v146, v114
	v_fmac_f32_e32 v12, v148, v116
	v_fmac_f32_e32 v12, v150, v118
	v_fmac_f32_e32 v12, v152, v120
	v_fmac_f32_e32 v12, v154, v122
	v_fmac_f32_e32 v12, v156, v124
	v_fmac_f32_e32 v12, v158, v126
	v_fmac_f32_e32 v12, v161, v129
	v_cndmask_b32_e64 v11, 0, -1.0, s[8:9]
	v_fmac_f32_e32 v11, v135, v103
	v_fmac_f32_e32 v11, v137, v105
	v_fmac_f32_e32 v11, v139, v107
	v_fmac_f32_e32 v11, v141, v109
	v_fmac_f32_e32 v11, v143, v111
	v_fmac_f32_e32 v11, v145, v113
	v_fmac_f32_e32 v11, v147, v115
	v_fmac_f32_e32 v11, v149, v117
	v_fmac_f32_e32 v11, v151, v119
	v_fmac_f32_e32 v11, v153, v121
	v_fmac_f32_e32 v11, v155, v123
	v_fmac_f32_e32 v11, v157, v125
	v_fmac_f32_e32 v11, v159, v127
	v_add_f32_e32 v11, v11, v12
	v_add_f32_dpp v8, v7, v7 quad_perm:[1,0,3,2] row_mask:0xf bank_mask:0xf
	v_cndmask_b32_e64 v128, v128, v8, s[98:99]
	v_cvt_pk_bf16_f32 v8, v8, v8
	ds_write_b16 v5, v8 offset:7200
	v_fma_f32 v7, -v160, v128, -v11
	ds_read_b128 v[134:137], v4 offset:13824
	ds_read_b128 v[138:141], v4 offset:13856
	ds_read_b128 v[142:145], v4 offset:13888
	ds_read_b128 v[146:149], v4 offset:13920
	ds_read_b128 v[150:153], v4 offset:13952
	ds_read_b128 v[154:157], v4 offset:13984
	ds_read_b128 v[158:161], v4 offset:14016
	s_waitcnt lgkmcnt(15)
	v_cmp_eq_u32_e64 s[8:9], 52, v6
	v_mul_f32_e32 v10, v202, v102
	v_fmac_f32_e32 v10, v204, v104
	v_fmac_f32_e32 v10, v206, v106
	v_fmac_f32_e32 v10, v208, v108
	v_fmac_f32_e32 v10, v210, v110
	v_fmac_f32_e32 v10, v212, v112
	v_fmac_f32_e32 v10, v220, v114
	v_fmac_f32_e32 v10, v222, v116
	v_fmac_f32_e32 v10, v224, v118
	v_fmac_f32_e32 v10, v226, v120
	v_fmac_f32_e32 v10, v228, v122
	v_fmac_f32_e32 v10, v230, v124
	v_fmac_f32_e32 v10, v232, v126
	v_fmac_f32_e32 v10, v234, v128
	v_cndmask_b32_e64 v9, 0, -1.0, s[8:9]
	v_fmac_f32_e32 v9, v203, v103
	v_fmac_f32_e32 v9, v205, v105
	v_fmac_f32_e32 v9, v207, v107
	v_fmac_f32_e32 v9, v209, v109
	v_fmac_f32_e32 v9, v211, v111
	v_fmac_f32_e32 v9, v213, v113
	v_fmac_f32_e32 v9, v221, v115
	v_fmac_f32_e32 v9, v223, v117
	v_fmac_f32_e32 v9, v225, v119
	v_fmac_f32_e32 v9, v227, v121
	v_fmac_f32_e32 v9, v229, v123
	v_fmac_f32_e32 v9, v231, v125
	v_fmac_f32_e32 v9, v233, v127
	v_add_f32_e32 v9, v9, v10
	v_add_f32_dpp v8, v7, v7 quad_perm:[1,0,3,2] row_mask:0xf bank_mask:0xf
	v_cndmask_b32_e64 v129, v129, v8, s[98:99]
	v_cvt_pk_bf16_f32 v8, v8, v8
	ds_write_b16 v5, v8 offset:7344
	v_fma_f32 v7, -v235, v129, -v9
	ds_read_b128 v[202:205], v4 offset:14080
	ds_read_b128 v[206:209], v4 offset:14112
	ds_read_b128 v[210:213], v4 offset:14144
	ds_read_b128 v[220:223], v4 offset:14176
	ds_read_b128 v[224:227], v4 offset:14208
	ds_read_b128 v[228:231], v4 offset:14240
	ds_read_b128 v[232:235], v4 offset:14272
	s_waitcnt lgkmcnt(15)
; #define LAS __attribute__((address_space(3)))
; __device__ __forceinline__ unsigned f2bf(float f) { unsigned u = __builtin_bit_cast(unsigned, f); return (u + 0x7fffu + ((u >> 16) & 1u)) >> 16; }
; __device__ __forceinline__ void gdn_prep_unit(Frame& F, int chain, int ci, unsigned char* rec, float* EGp, unsigned* qctr) {
;     ...
;         for (int c = 0; c < 64; ++c) {
;             float a0 = 0.f, a1 = 0.f, a2 = 0.f, a3 = 0.f;
; #pragma unroll
;             for (int k = 0; k < ((c + 3) / 4 + 1) / 2; ++k) { const f32x4 l4 = *(const LAS f32x4*)(Lrow + c * 256 + k * 32);
;                 a0 += l4.x * Tm[k][0]; a1 += l4.y * Tm[k][1]; a2 += l4.z * Tm[k][2]; a3 += l4.w * Tm[k][3]; }
;             float a = (a0 + a1) + (a2 + a3);
;             a += __builtin_bit_cast(float, __builtin_amdgcn_update_dpp(0, __builtin_bit_cast(int, a), 0xB1, 0xF, 0xF, false));
;             const float tn = ((c == j) ? 1.f : 0.f) - a;
;             Tm[c >> 3][c & 3] = (((c >> 2) & 1) == hh2) ? tn : Tm[c >> 3][c & 3];
;             if (hh2 == 0) *(LAS bf16*)(L + PL_TT + c * 144 + j * 2) = (bf16)f2bf(tn);
;         }
	v_cmp_eq_u32_e64 s[8:9], 53, v6
	v_mul_f32_e32 v12, v166, v102
	v_fmac_f32_e32 v12, v168, v104
	v_fmac_f32_e32 v12, v170, v106
	v_fmac_f32_e32 v12, v172, v108
	v_fmac_f32_e32 v12, v174, v110
	v_fmac_f32_e32 v12, v176, v112
	v_fmac_f32_e32 v12, v178, v114
	v_fmac_f32_e32 v12, v180, v116
	v_fmac_f32_e32 v12, v182, v118
	v_fmac_f32_e32 v12, v184, v120
	v_fmac_f32_e32 v12, v186, v122
	v_fmac_f32_e32 v12, v188, v124
	v_fmac_f32_e32 v12, v191, v127
	v_fmac_f32_e32 v12, v193, v129
	v_cndmask_b32_e64 v11, 0, -1.0, s[8:9]
	v_fmac_f32_e32 v11, v167, v103
	v_fmac_f32_e32 v11, v169, v105
	v_fmac_f32_e32 v11, v171, v107
	v_fmac_f32_e32 v11, v173, v109
	v_fmac_f32_e32 v11, v175, v111
	v_fmac_f32_e32 v11, v177, v113
	v_fmac_f32_e32 v11, v179, v115
	v_fmac_f32_e32 v11, v181, v117
	v_fmac_f32_e32 v11, v183, v119
	v_fmac_f32_e32 v11, v185, v121
	v_fmac_f32_e32 v11, v187, v123
	v_fmac_f32_e32 v11, v189, v125
	v_fmac_f32_e32 v11, v192, v128
	v_add_f32_e32 v11, v11, v12
	v_add_f32_dpp v8, v7, v7 quad_perm:[1,0,3,2] row_mask:0xf bank_mask:0xf
	v_cndmask_b32_e64 v126, v126, v8, s[100:101]
	v_cvt_pk_bf16_f32 v8, v8, v8
	ds_write_b16 v5, v8 offset:7488
	v_fma_f32 v7, -v190, v126, -v11
	ds_read_b128 v[166:169], v4 offset:14336
	ds_read_b128 v[170:173], v4 offset:14368
	ds_read_b128 v[174:177], v4 offset:14400
	ds_read_b128 v[178:181], v4 offset:14432
	ds_read_b128 v[182:185], v4 offset:14464
	ds_read_b128 v[186:189], v4 offset:14496
	ds_read_b128 v[190:193], v4 offset:14528
	s_waitcnt lgkmcnt(15)
	v_cmp_eq_u32_e64 s[8:9], 54, v6
	v_mul_f32_e32 v10, v134, v102
	v_fmac_f32_e32 v10, v136, v104
	v_fmac_f32_e32 v10, v138, v106
	v_fmac_f32_e32 v10, v140, v108
	v_fmac_f32_e32 v10, v142, v110
	v_fmac_f32_e32 v10, v144, v112
	v_fmac_f32_e32 v10, v146, v114
	v_fmac_f32_e32 v10, v148, v116
	v_fmac_f32_e32 v10, v150, v118
	v_fmac_f32_e32 v10, v152, v120
	v_fmac_f32_e32 v10, v154, v122
	v_fmac_f32_e32 v10, v156, v124
	v_fmac_f32_e32 v10, v158, v126
	v_fmac_f32_e32 v10, v161, v129
	v_cndmask_b32_e64 v9, 0, -1.0, s[8:9]
	v_fmac_f32_e32 v9, v135, v103
	v_fmac_f32_e32 v9, v137, v105
	v_fmac_f32_e32 v9, v139, v107
	v_fmac_f32_e32 v9, v141, v109
	v_fmac_f32_e32 v9, v143, v111
	v_fmac_f32_e32 v9, v145, v113
	v_fmac_f32_e32 v9, v147, v115
	v_fmac_f32_e32 v9, v149, v117
	v_fmac_f32_e32 v9, v151, v119
	v_fmac_f32_e32 v9, v153, v121
	v_fmac_f32_e32 v9, v155, v123
	v_fmac_f32_e32 v9, v157, v125
	v_fmac_f32_e32 v9, v160, v128
	v_add_f32_e32 v9, v9, v10
	v_add_f32_dpp v8, v7, v7 quad_perm:[1,0,3,2] row_mask:0xf bank_mask:0xf
	v_cndmask_b32_e64 v127, v127, v8, s[100:101]
	v_cvt_pk_bf16_f32 v8, v8, v8
	ds_write_b16 v5, v8 offset:7632
	v_fma_f32 v7, -v159, v127, -v9
	ds_read_b128 v[134:137], v4 offset:14592
	ds_read_b128 v[138:141], v4 offset:14624
	ds_read_b128 v[142:145], v4 offset:14656
	ds_read_b128 v[146:149], v4 offset:14688
	ds_read_b128 v[150:153], v4 offset:14720
	ds_read_b128 v[154:157], v4 offset:14752
	ds_read_b128 v[158:161], v4 offset:14784
	ds_read_b128 v[162:165], v4 offset:14816
	s_waitcnt lgkmcnt(15)
	v_cmp_eq_u32_e64 s[8:9], 55, v6
	v_mul_f32_e32 v12, v202, v102
	v_fmac_f32_e32 v12, v204, v104
	v_fmac_f32_e32 v12, v206, v106
	v_fmac_f32_e32 v12, v208, v108
	v_fmac_f32_e32 v12, v210, v110
	v_fmac_f32_e32 v12, v212, v112
	v_fmac_f32_e32 v12, v220, v114
	v_fmac_f32_e32 v12, v222, v116
	v_fmac_f32_e32 v12, v224, v118
	v_fmac_f32_e32 v12, v226, v120
	v_fmac_f32_e32 v12, v228, v122
	v_fmac_f32_e32 v12, v230, v124
	v_fmac_f32_e32 v12, v232, v126
	v_fmac_f32_e32 v12, v235, v129
	v_cndmask_b32_e64 v11, 0, -1.0, s[8:9]
	v_fmac_f32_e32 v11, v203, v103
	v_fmac_f32_e32 v11, v205, v105
	v_fmac_f32_e32 v11, v207, v107
	v_fmac_f32_e32 v11, v209, v109
	v_fmac_f32_e32 v11, v211, v111
	v_fmac_f32_e32 v11, v213, v113
	v_fmac_f32_e32 v11, v221, v115
	v_fmac_f32_e32 v11, v223, v117
	v_fmac_f32_e32 v11, v225, v119
	v_fmac_f32_e32 v11, v227, v121
	v_fmac_f32_e32 v11, v229, v123
	v_fmac_f32_e32 v11, v231, v125
	v_fmac_f32_e32 v11, v233, v127
	v_add_f32_e32 v11, v11, v12
	v_add_f32_dpp v8, v7, v7 quad_perm:[1,0,3,2] row_mask:0xf bank_mask:0xf
	v_cndmask_b32_e64 v128, v128, v8, s[100:101]
	v_cvt_pk_bf16_f32 v8, v8, v8
	ds_write_b16 v5, v8 offset:7776
	v_fma_f32 v7, -v234, v128, -v11
	ds_read_b128 v[202:205], v4 offset:14848
	ds_read_b128 v[206:209], v4 offset:14880
	ds_read_b128 v[210:213], v4 offset:14912
	ds_read_b128 v[220:223], v4 offset:14944
	ds_read_b128 v[224:227], v4 offset:14976
	ds_read_b128 v[228:231], v4 offset:15008
	ds_read_b128 v[232:235], v4 offset:15040
	ds_read_b128 v[238:241], v4 offset:15072
	s_waitcnt lgkmcnt(15)
	v_cmp_eq_u32_e64 s[8:9], 56, v6
	v_mul_f32_e32 v10, v166, v102
	v_fmac_f32_e32 v10, v168, v104
	v_fmac_f32_e32 v10, v170, v106
	v_fmac_f32_e32 v10, v172, v108
	v_fmac_f32_e32 v10, v174, v110
	v_fmac_f32_e32 v10, v176, v112
	v_fmac_f32_e32 v10, v178, v114
	v_fmac_f32_e32 v10, v180, v116
	v_fmac_f32_e32 v10, v182, v118
	v_fmac_f32_e32 v10, v184, v120
	v_fmac_f32_e32 v10, v186, v122
	v_fmac_f32_e32 v10, v188, v124
	v_fmac_f32_e32 v10, v190, v126
	v_fmac_f32_e32 v10, v192, v128
	v_cndmask_b32_e64 v9, 0, -1.0, s[8:9]
	v_fmac_f32_e32 v9, v167, v103
	v_fmac_f32_e32 v9, v169, v105
	v_fmac_f32_e32 v9, v171, v107
	v_fmac_f32_e32 v9, v173, v109
	v_fmac_f32_e32 v9, v175, v111
	v_fmac_f32_e32 v9, v177, v113
	v_fmac_f32_e32 v9, v179, v115
	v_fmac_f32_e32 v9, v181, v117
	v_fmac_f32_e32 v9, v183, v119
	v_fmac_f32_e32 v9, v185, v121
	v_fmac_f32_e32 v9, v187, v123
	v_fmac_f32_e32 v9, v189, v125
	v_fmac_f32_e32 v9, v191, v127
	v_add_f32_e32 v9, v9, v10
	v_add_f32_dpp v8, v7, v7 quad_perm:[1,0,3,2] row_mask:0xf bank_mask:0xf
	v_cndmask_b32_e64 v129, v129, v8, s[100:101]
	v_cvt_pk_bf16_f32 v8, v8, v8
	ds_write_b16 v5, v8 offset:7920
	v_fma_f32 v7, -v193, v129, -v9
	ds_read_b128 v[166:169], v4 offset:15104
	ds_read_b128 v[170:173], v4 offset:15136
	ds_read_b128 v[174:177], v4 offset:15168
	ds_read_b128 v[178:181], v4 offset:15200
	ds_read_b128 v[182:185], v4 offset:15232
	ds_read_b128 v[186:189], v4 offset:15264
	ds_read_b128 v[190:193], v4 offset:15296
	ds_read_b128 v[242:245], v4 offset:15328
	s_waitcnt lgkmcnt(15)
; #define LAS __attribute__((address_space(3)))
; __device__ __forceinline__ unsigned f2bf(float f) { unsigned u = __builtin_bit_cast(unsigned, f); return (u + 0x7fffu + ((u >> 16) & 1u)) >> 16; }
; __device__ __forceinline__ void gdn_prep_unit(Frame& F, int chain, int ci, unsigned char* rec, float* EGp, unsigned* qctr) {
;     ...
;         for (int c = 0; c < 64; ++c) {
;             float a0 = 0.f, a1 = 0.f, a2 = 0.f, a3 = 0.f;
; #pragma unroll
;             for (int k = 0; k < ((c + 3) / 4 + 1) / 2; ++k) { const f32x4 l4 = *(const LAS f32x4*)(Lrow + c * 256 + k * 32);
;                 a0 += l4.x * Tm[k][0]; a1 += l4.y * Tm[k][1]; a2 += l4.z * Tm[k][2]; a3 += l4.w * Tm[k][3]; }
;             float a = (a0 + a1) + (a2 + a3);
;             a += __builtin_bit_cast(float, __builtin_amdgcn_update_dpp(0, __builtin_bit_cast(int, a), 0xB1, 0xF, 0xF, false));
;             const float tn = ((c == j) ? 1.f : 0.f) - a;
;             Tm[c >> 3][c & 3] = (((c >> 2) & 1) == hh2) ? tn : Tm[c >> 3][c & 3];
;             if (hh2 == 0) *(LAS bf16*)(L + PL_TT + c * 144 + j * 2) = (bf16)f2bf(tn);
;         }
	v_cmp_eq_u32_e64 s[8:9], 57, v6
	v_mul_f32_e32 v12, v134, v102
	v_fmac_f32_e32 v12, v136, v104
	v_fmac_f32_e32 v12, v138, v106
	v_fmac_f32_e32 v12, v140, v108
	v_fmac_f32_e32 v12, v142, v110
	v_fmac_f32_e32 v12, v144, v112
	v_fmac_f32_e32 v12, v146, v114
	v_fmac_f32_e32 v12, v148, v116
	v_fmac_f32_e32 v12, v150, v118
	v_fmac_f32_e32 v12, v152, v120
	v_fmac_f32_e32 v12, v154, v122
	v_fmac_f32_e32 v12, v156, v124
	v_fmac_f32_e32 v12, v158, v126
	v_fmac_f32_e32 v12, v160, v128
	v_fmac_f32_e32 v12, v163, v131
	v_fmac_f32_e32 v12, v165, v133
	v_cndmask_b32_e64 v11, 0, -1.0, s[8:9]
	v_fmac_f32_e32 v11, v135, v103
	v_fmac_f32_e32 v11, v137, v105
	v_fmac_f32_e32 v11, v139, v107
	v_fmac_f32_e32 v11, v141, v109
	v_fmac_f32_e32 v11, v143, v111
	v_fmac_f32_e32 v11, v145, v113
	v_fmac_f32_e32 v11, v147, v115
	v_fmac_f32_e32 v11, v149, v117
	v_fmac_f32_e32 v11, v151, v119
	v_fmac_f32_e32 v11, v153, v121
	v_fmac_f32_e32 v11, v155, v123
	v_fmac_f32_e32 v11, v157, v125
	v_fmac_f32_e32 v11, v159, v127
	v_fmac_f32_e32 v11, v161, v129
	v_fmac_f32_e32 v11, v164, v132
	v_add_f32_e32 v11, v11, v12
	v_add_f32_dpp v8, v7, v7 quad_perm:[1,0,3,2] row_mask:0xf bank_mask:0xf
	v_cndmask_b32_e64 v130, v130, v8, s[98:99]
	v_cvt_pk_bf16_f32 v8, v8, v8
	ds_write_b16 v5, v8 offset:8064
	v_fma_f32 v7, -v162, v130, -v11
	ds_read_b128 v[134:137], v4 offset:15360
	ds_read_b128 v[138:141], v4 offset:15392
	ds_read_b128 v[142:145], v4 offset:15424
	ds_read_b128 v[146:149], v4 offset:15456
	ds_read_b128 v[150:153], v4 offset:15488
	ds_read_b128 v[154:157], v4 offset:15520
	ds_read_b128 v[158:161], v4 offset:15552
	ds_read_b128 v[162:165], v4 offset:15584
	s_waitcnt lgkmcnt(15)
	v_cmp_eq_u32_e64 s[8:9], 58, v6
	v_mul_f32_e32 v10, v202, v102
	v_fmac_f32_e32 v10, v204, v104
	v_fmac_f32_e32 v10, v206, v106
	v_fmac_f32_e32 v10, v208, v108
	v_fmac_f32_e32 v10, v210, v110
	v_fmac_f32_e32 v10, v212, v112
	v_fmac_f32_e32 v10, v220, v114
	v_fmac_f32_e32 v10, v222, v116
	v_fmac_f32_e32 v10, v224, v118
	v_fmac_f32_e32 v10, v226, v120
	v_fmac_f32_e32 v10, v228, v122
	v_fmac_f32_e32 v10, v230, v124
	v_fmac_f32_e32 v10, v232, v126
	v_fmac_f32_e32 v10, v234, v128
	v_fmac_f32_e32 v10, v238, v130
	v_fmac_f32_e32 v10, v241, v133
	v_cndmask_b32_e64 v9, 0, -1.0, s[8:9]
	v_fmac_f32_e32 v9, v203, v103
	v_fmac_f32_e32 v9, v205, v105
	v_fmac_f32_e32 v9, v207, v107
	v_fmac_f32_e32 v9, v209, v109
	v_fmac_f32_e32 v9, v211, v111
	v_fmac_f32_e32 v9, v213, v113
	v_fmac_f32_e32 v9, v221, v115
	v_fmac_f32_e32 v9, v223, v117
	v_fmac_f32_e32 v9, v225, v119
	v_fmac_f32_e32 v9, v227, v121
	v_fmac_f32_e32 v9, v229, v123
	v_fmac_f32_e32 v9, v231, v125
	v_fmac_f32_e32 v9, v233, v127
	v_fmac_f32_e32 v9, v235, v129
	v_fmac_f32_e32 v9, v240, v132
	v_add_f32_e32 v9, v9, v10
	v_add_f32_dpp v8, v7, v7 quad_perm:[1,0,3,2] row_mask:0xf bank_mask:0xf
	v_cndmask_b32_e64 v131, v131, v8, s[98:99]
	v_cvt_pk_bf16_f32 v8, v8, v8
	ds_write_b16 v5, v8 offset:8208
	v_fma_f32 v7, -v239, v131, -v9
	ds_read_b128 v[202:205], v4 offset:15616
	ds_read_b128 v[206:209], v4 offset:15648
	ds_read_b128 v[210:213], v4 offset:15680
	ds_read_b128 v[220:223], v4 offset:15712
	ds_read_b128 v[224:227], v4 offset:15744
	ds_read_b128 v[228:231], v4 offset:15776
	ds_read_b128 v[232:235], v4 offset:15808
	ds_read_b128 v[238:241], v4 offset:15840
	s_waitcnt lgkmcnt(15)
	v_cmp_eq_u32_e64 s[8:9], 59, v6
	v_mul_f32_e32 v12, v166, v102
	v_fmac_f32_e32 v12, v168, v104
	v_fmac_f32_e32 v12, v170, v106
	v_fmac_f32_e32 v12, v172, v108
	v_fmac_f32_e32 v12, v174, v110
	v_fmac_f32_e32 v12, v176, v112
	v_fmac_f32_e32 v12, v178, v114
	v_fmac_f32_e32 v12, v180, v116
	v_fmac_f32_e32 v12, v182, v118
	v_fmac_f32_e32 v12, v184, v120
	v_fmac_f32_e32 v12, v186, v122
	v_fmac_f32_e32 v12, v188, v124
	v_fmac_f32_e32 v12, v190, v126
	v_fmac_f32_e32 v12, v192, v128
	v_fmac_f32_e32 v12, v242, v130
	v_fmac_f32_e32 v12, v245, v133
	v_cndmask_b32_e64 v11, 0, -1.0, s[8:9]
	v_fmac_f32_e32 v11, v167, v103
	v_fmac_f32_e32 v11, v169, v105
	v_fmac_f32_e32 v11, v171, v107
	v_fmac_f32_e32 v11, v173, v109
	v_fmac_f32_e32 v11, v175, v111
	v_fmac_f32_e32 v11, v177, v113
	v_fmac_f32_e32 v11, v179, v115
	v_fmac_f32_e32 v11, v181, v117
	v_fmac_f32_e32 v11, v183, v119
	v_fmac_f32_e32 v11, v185, v121
	v_fmac_f32_e32 v11, v187, v123
	v_fmac_f32_e32 v11, v189, v125
	v_fmac_f32_e32 v11, v191, v127
	v_fmac_f32_e32 v11, v193, v129
	v_fmac_f32_e32 v11, v243, v131
	v_add_f32_e32 v11, v11, v12
	v_add_f32_dpp v8, v7, v7 quad_perm:[1,0,3,2] row_mask:0xf bank_mask:0xf
	v_cndmask_b32_e64 v132, v132, v8, s[98:99]
	v_cvt_pk_bf16_f32 v8, v8, v8
	ds_write_b16 v5, v8 offset:8352
	v_fma_f32 v7, -v244, v132, -v11
	ds_read_b128 v[166:169], v4 offset:15872
	ds_read_b128 v[170:173], v4 offset:15904
	ds_read_b128 v[174:177], v4 offset:15936
	ds_read_b128 v[178:181], v4 offset:15968
	ds_read_b128 v[182:185], v4 offset:16000
	ds_read_b128 v[186:189], v4 offset:16032
	ds_read_b128 v[190:193], v4 offset:16064
	ds_read_b128 v[242:245], v4 offset:16096
	s_waitcnt lgkmcnt(15)
; #define LAS __attribute__((address_space(3)))
; __device__ __forceinline__ unsigned f2bf(float f) { unsigned u = __builtin_bit_cast(unsigned, f); return (u + 0x7fffu + ((u >> 16) & 1u)) >> 16; }
; __device__ __forceinline__ void gdn_prep_unit(Frame& F, int chain, int ci, unsigned char* rec, float* EGp, unsigned* qctr) {
;     ...
;         for (int c = 0; c < 64; ++c) {
;             float a0 = 0.f, a1 = 0.f, a2 = 0.f, a3 = 0.f;
; #pragma unroll
;             for (int k = 0; k < ((c + 3) / 4 + 1) / 2; ++k) { const f32x4 l4 = *(const LAS f32x4*)(Lrow + c * 256 + k * 32);
;                 a0 += l4.x * Tm[k][0]; a1 += l4.y * Tm[k][1]; a2 += l4.z * Tm[k][2]; a3 += l4.w * Tm[k][3]; }
;             float a = (a0 + a1) + (a2 + a3);
;             a += __builtin_bit_cast(float, __builtin_amdgcn_update_dpp(0, __builtin_bit_cast(int, a), 0xB1, 0xF, 0xF, false));
;             const float tn = ((c == j) ? 1.f : 0.f) - a;
;             Tm[c >> 3][c & 3] = (((c >> 2) & 1) == hh2) ? tn : Tm[c >> 3][c & 3];
;             if (hh2 == 0) *(LAS bf16*)(L + PL_TT + c * 144 + j * 2) = (bf16)f2bf(tn);
;         }
;         if (F.wave == 0) F.MISC[16] = 1u;
	v_cmp_eq_u32_e64 s[8:9], 60, v6
	v_mul_f32_e32 v10, v134, v102
	v_fmac_f32_e32 v10, v136, v104
	v_fmac_f32_e32 v10, v138, v106
	v_fmac_f32_e32 v10, v140, v108
	v_fmac_f32_e32 v10, v142, v110
	v_fmac_f32_e32 v10, v144, v112
	v_fmac_f32_e32 v10, v146, v114
	v_fmac_f32_e32 v10, v148, v116
	v_fmac_f32_e32 v10, v150, v118
	v_fmac_f32_e32 v10, v152, v120
	v_fmac_f32_e32 v10, v154, v122
	v_fmac_f32_e32 v10, v156, v124
	v_fmac_f32_e32 v10, v158, v126
	v_fmac_f32_e32 v10, v160, v128
	v_fmac_f32_e32 v10, v162, v130
	v_fmac_f32_e32 v10, v164, v132
	v_cndmask_b32_e64 v9, 0, -1.0, s[8:9]
	v_fmac_f32_e32 v9, v135, v103
	v_fmac_f32_e32 v9, v137, v105
	v_fmac_f32_e32 v9, v139, v107
	v_fmac_f32_e32 v9, v141, v109
	v_fmac_f32_e32 v9, v143, v111
	v_fmac_f32_e32 v9, v145, v113
	v_fmac_f32_e32 v9, v147, v115
	v_fmac_f32_e32 v9, v149, v117
	v_fmac_f32_e32 v9, v151, v119
	v_fmac_f32_e32 v9, v153, v121
	v_fmac_f32_e32 v9, v155, v123
	v_fmac_f32_e32 v9, v157, v125
	v_fmac_f32_e32 v9, v159, v127
	v_fmac_f32_e32 v9, v161, v129
	v_fmac_f32_e32 v9, v163, v131
	v_add_f32_e32 v9, v9, v10
	v_add_f32_dpp v8, v7, v7 quad_perm:[1,0,3,2] row_mask:0xf bank_mask:0xf
	v_cndmask_b32_e64 v133, v133, v8, s[98:99]
	v_cvt_pk_bf16_f32 v8, v8, v8
	ds_write_b16 v5, v8 offset:8496
	v_fma_f32 v7, -v165, v133, -v9
	ds_read_b128 v[134:137], v4 offset:16128
	ds_read_b128 v[138:141], v4 offset:16160
	ds_read_b128 v[142:145], v4 offset:16192
	ds_read_b128 v[146:149], v4 offset:16224
	ds_read_b128 v[150:153], v4 offset:16256
	ds_read_b128 v[154:157], v4 offset:16288
	ds_read_b128 v[158:161], v4 offset:16320
	ds_read_b128 v[162:165], v4 offset:16352
	s_waitcnt lgkmcnt(15)
	v_cmp_eq_u32_e64 s[8:9], 61, v6
	v_mul_f32_e32 v12, v202, v102
	v_fmac_f32_e32 v12, v204, v104
	v_fmac_f32_e32 v12, v206, v106
	v_fmac_f32_e32 v12, v208, v108
	v_fmac_f32_e32 v12, v210, v110
	v_fmac_f32_e32 v12, v212, v112
	v_fmac_f32_e32 v12, v220, v114
	v_fmac_f32_e32 v12, v222, v116
	v_fmac_f32_e32 v12, v224, v118
	v_fmac_f32_e32 v12, v226, v120
	v_fmac_f32_e32 v12, v228, v122
	v_fmac_f32_e32 v12, v230, v124
	v_fmac_f32_e32 v12, v232, v126
	v_fmac_f32_e32 v12, v234, v128
	v_fmac_f32_e32 v12, v239, v131
	v_fmac_f32_e32 v12, v241, v133
	v_cndmask_b32_e64 v11, 0, -1.0, s[8:9]
	v_fmac_f32_e32 v11, v203, v103
	v_fmac_f32_e32 v11, v205, v105
	v_fmac_f32_e32 v11, v207, v107
	v_fmac_f32_e32 v11, v209, v109
	v_fmac_f32_e32 v11, v211, v111
	v_fmac_f32_e32 v11, v213, v113
	v_fmac_f32_e32 v11, v221, v115
	v_fmac_f32_e32 v11, v223, v117
	v_fmac_f32_e32 v11, v225, v119
	v_fmac_f32_e32 v11, v227, v121
	v_fmac_f32_e32 v11, v229, v123
	v_fmac_f32_e32 v11, v231, v125
	v_fmac_f32_e32 v11, v233, v127
	v_fmac_f32_e32 v11, v235, v129
	v_fmac_f32_e32 v11, v240, v132
	v_add_f32_e32 v11, v11, v12
	v_add_f32_dpp v8, v7, v7 quad_perm:[1,0,3,2] row_mask:0xf bank_mask:0xf
	v_cndmask_b32_e64 v130, v130, v8, s[100:101]
	v_cvt_pk_bf16_f32 v8, v8, v8
	ds_write_b16 v5, v8 offset:8640
	v_fma_f32 v7, -v238, v130, -v11
	s_waitcnt lgkmcnt(10)
	v_cmp_eq_u32_e64 s[8:9], 62, v6
	v_mul_f32_e32 v10, v166, v102
	v_fmac_f32_e32 v10, v168, v104
	v_fmac_f32_e32 v10, v170, v106
	v_fmac_f32_e32 v10, v172, v108
	v_fmac_f32_e32 v10, v174, v110
	v_fmac_f32_e32 v10, v176, v112
	v_fmac_f32_e32 v10, v178, v114
	v_fmac_f32_e32 v10, v180, v116
	v_fmac_f32_e32 v10, v182, v118
	v_fmac_f32_e32 v10, v184, v120
	v_fmac_f32_e32 v10, v186, v122
	v_fmac_f32_e32 v10, v188, v124
	v_fmac_f32_e32 v10, v190, v126
	v_fmac_f32_e32 v10, v192, v128
	v_fmac_f32_e32 v10, v242, v130
	v_fmac_f32_e32 v10, v245, v133
	v_cndmask_b32_e64 v9, 0, -1.0, s[8:9]
	v_fmac_f32_e32 v9, v167, v103
	v_fmac_f32_e32 v9, v169, v105
	v_fmac_f32_e32 v9, v171, v107
	v_fmac_f32_e32 v9, v173, v109
	v_fmac_f32_e32 v9, v175, v111
	v_fmac_f32_e32 v9, v177, v113
	v_fmac_f32_e32 v9, v179, v115
	v_fmac_f32_e32 v9, v181, v117
	v_fmac_f32_e32 v9, v183, v119
	v_fmac_f32_e32 v9, v185, v121
	v_fmac_f32_e32 v9, v187, v123
	v_fmac_f32_e32 v9, v189, v125
	v_fmac_f32_e32 v9, v191, v127
	v_fmac_f32_e32 v9, v193, v129
	v_fmac_f32_e32 v9, v244, v132
	v_add_f32_e32 v9, v9, v10
	v_add_f32_dpp v8, v7, v7 quad_perm:[1,0,3,2] row_mask:0xf bank_mask:0xf
	v_cndmask_b32_e64 v131, v131, v8, s[100:101]
	v_cvt_pk_bf16_f32 v8, v8, v8
	ds_write_b16 v5, v8 offset:8784
	v_fma_f32 v7, -v243, v131, -v9
	s_waitcnt lgkmcnt(2)
	v_cmp_eq_u32_e64 s[8:9], 63, v6
	v_mul_f32_e32 v12, v134, v102
	v_fmac_f32_e32 v12, v136, v104
	v_fmac_f32_e32 v12, v138, v106
	v_fmac_f32_e32 v12, v140, v108
	v_fmac_f32_e32 v12, v142, v110
	v_fmac_f32_e32 v12, v144, v112
	v_fmac_f32_e32 v12, v146, v114
	v_fmac_f32_e32 v12, v148, v116
	v_fmac_f32_e32 v12, v150, v118
	v_fmac_f32_e32 v12, v152, v120
	v_fmac_f32_e32 v12, v154, v122
	v_fmac_f32_e32 v12, v156, v124
	v_fmac_f32_e32 v12, v158, v126
	v_fmac_f32_e32 v12, v160, v128
	v_fmac_f32_e32 v12, v162, v130
	v_fmac_f32_e32 v12, v165, v133
	v_cndmask_b32_e64 v11, 0, -1.0, s[8:9]
	v_fmac_f32_e32 v11, v135, v103
	v_fmac_f32_e32 v11, v137, v105
	v_fmac_f32_e32 v11, v139, v107
	v_fmac_f32_e32 v11, v141, v109
	v_fmac_f32_e32 v11, v143, v111
	v_fmac_f32_e32 v11, v145, v113
	v_fmac_f32_e32 v11, v147, v115
	v_fmac_f32_e32 v11, v149, v117
	v_fmac_f32_e32 v11, v151, v119
	v_fmac_f32_e32 v11, v153, v121
	v_fmac_f32_e32 v11, v155, v123
	v_fmac_f32_e32 v11, v157, v125
	v_fmac_f32_e32 v11, v159, v127
	v_fmac_f32_e32 v11, v161, v129
	v_fmac_f32_e32 v11, v163, v131
	v_add_f32_e32 v11, v11, v12
	v_add_f32_dpp v8, v7, v7 quad_perm:[1,0,3,2] row_mask:0xf bank_mask:0xf
	v_cndmask_b32_e64 v132, v132, v8, s[100:101]
	v_cvt_pk_bf16_f32 v8, v8, v8
	ds_write_b16 v5, v8 offset:8928
	v_fma_f32 v7, -v164, v132, -v11
	s_nop 1
	v_add_f32_dpp v8, v7, v7 quad_perm:[1,0,3,2] row_mask:0xf bank_mask:0xf
	v_cndmask_b32_e64 v133, v133, v8, s[100:101]
	v_cvt_pk_bf16_f32 v8, v8, v8
	ds_write_b16 v5, v8 offset:9072

; #define LAS __attribute__((address_space(3)))
; __device__ __forceinline__ unsigned f2bf(float f) { unsigned u = __builtin_bit_cast(unsigned, f); return (u + 0x7fffu + ((u >> 16) & 1u)) >> 16; }
; __device__ __forceinline__ void gdn_prep_unit(Frame& F, int chain, int ci, unsigned char* rec, float* EGp, unsigned* qctr) {
;     ...
;     if (F.wave < 2) {
;         const int hh2 = lane & 1, j = 32 * F.wave + (lane >> 1);
;         LAS unsigned char* Lrow = (LAS unsigned char*)LOW + hh2 * 16;
;         float Tm[8][4];
; #pragma unroll
;         for (int k = 0; k < 8; ++k) { Tm[k][0] = 0.f; Tm[k][1] = 0.f; Tm[k][2] = 0.f; Tm[k][3] = 0.f; }
; #pragma unroll
;         for (int c = 0; c < 64; ++c) {
;             float a0 = 0.f, a1 = 0.f, a2 = 0.f, a3 = 0.f;
; #pragma unroll
;             for (int k = 0; k < ((c + 3) / 4 + 1) / 2; ++k) { const f32x4 l4 = *(const LAS f32x4*)(Lrow + c * 256 + k * 32);
;                 a0 += l4.x * Tm[k][0]; a1 += l4.y * Tm[k][1]; a2 += l4.z * Tm[k][2]; a3 += l4.w * Tm[k][3]; }
;             float a = (a0 + a1) + (a2 + a3);
;             a += __builtin_bit_cast(float, __builtin_amdgcn_update_dpp(0, __builtin_bit_cast(int, a), 0xB1, 0xF, 0xF, false));
;             const float tn = ((c == j) ? 1.f : 0.f) - a;
;             Tm[c >> 3][c & 3] = (((c >> 2) & 1) == hh2) ? tn : Tm[c >> 3][c & 3];
;             if (hh2 == 0) *(LAS bf16*)(L + PL_TT + c * 144 + j * 2) = (bf16)f2bf(tn);
;         }
;         if (F.wave == 0) F.MISC[16] = 1u;
;     }
	.amdhsa_kernel _Z9hymba_fwd4Args
		.amdhsa_group_segment_fixed_size 0
		.amdhsa_private_segment_fixed_size 0
		.amdhsa_kernarg_size 504
		.amdhsa_user_sgpr_count 2
		.amdhsa_user_sgpr_dispatch_ptr 0
		.amdhsa_user_sgpr_queue_ptr 0
		.amdhsa_user_sgpr_kernarg_segment_ptr 1
		.amdhsa_user_sgpr_dispatch_id 0
		.amdhsa_user_sgpr_kernarg_preload_length 0
		.amdhsa_user_sgpr_kernarg_preload_offset 0
		.amdhsa_user_sgpr_private_segment_size 0
		.amdhsa_uses_dynamic_stack 0
		.amdhsa_enable_private_segment 0
		.amdhsa_system_sgpr_workgroup_id_x 1
		.amdhsa_system_sgpr_workgroup_id_y 0
		.amdhsa_system_sgpr_workgroup_id_z 0
		.amdhsa_system_sgpr_workgroup_info 0
		.amdhsa_system_vgpr_workitem_id 0
		.amdhsa_next_free_vgpr 256
		.amdhsa_next_free_sgpr 102
		.amdhsa_accum_offset 256
		.amdhsa_reserve_vcc 1
		.amdhsa_float_round_mode_32 0
		.amdhsa_float_round_mode_16_64 0
		.amdhsa_float_denorm_mode_32 3
		.amdhsa_float_denorm_mode_16_64 3
		.amdhsa_dx10_clamp 1
		.amdhsa_ieee_mode 1
		.amdhsa_fp16_overflow 0
		.amdhsa_tg_split 0
		.amdhsa_exception_fp_ieee_invalid_op 0
		.amdhsa_exception_fp_denorm_src 0
		.amdhsa_exception_fp_ieee_div_zero 0
		.amdhsa_exception_fp_ieee_overflow 0
		.amdhsa_exception_fp_ieee_underflow 0
		.amdhsa_exception_fp_ieee_inexact 0
		.amdhsa_exception_int_div_zero 0
	.end_amdhsa_kernel

; #define LAS __attribute__((address_space(3)))
; __global__ void __launch_bounds__(NWAVES * 64, 2) hymba_fwd(Args args) {
;     extern __shared__ __attribute__((aligned(16))) unsigned char lds[];
;     Frame F;
;     F.lds = (LAS unsigned char*)lds;
;     F.MISC = (volatile LAS unsigned*)(F.lds + MISC_OFF);
;     F.tid = threadIdx.x; F.lane = F.tid & 63; F.wave = __builtin_amdgcn_readfirstlane(F.tid >> 6);
;     F.G = gridDim.x; F.bid = blockIdx.x;
;     F.ws = args.ws; F.ctl = (unsigned*)(args.ws + WS_CTL); F.out = args.out;
;     for (int u = F.tid; u < (LDS_BYTES - LDSCTL_OFF) / 4; u += NWAVES * 64) ((LAS unsigned*)(F.lds + LDSCTL_OFF))[u] = 0u;
;     __syncthreads();
;     XcdBarrier bar; bar.bar = F.ctl + CW_BAR; bar.x = 0; bar.st = nullptr;
;     if (N_LAUNCHES == 1) bar = xcd_barrier_post(F.ctl + CW_BAR, F.MISC + 8);
amdhsa.kernels:
  - .agpr_count:     0
    .args:
      - .offset:         0
        .size:           248
        .value_kind:     by_value
      - .offset:         248
        .size:           4
        .value_kind:     hidden_block_count_x
      - .offset:         252
        .size:           4
        .value_kind:     hidden_block_count_y
      - .offset:         256
        .size:           4
        .value_kind:     hidden_block_count_z
      - .offset:         260
        .size:           2
        .value_kind:     hidden_group_size_x
      - .offset:         262
        .size:           2
        .value_kind:     hidden_group_size_y
      - .offset:         264
        .size:           2
        .value_kind:     hidden_group_size_z
      - .offset:         266
        .size:           2
        .value_kind:     hidden_remainder_x
      - .offset:         268
        .size:           2
        .value_kind:     hidden_remainder_y
      - .offset:         270
        .size:           2
        .value_kind:     hidden_remainder_z
      - .offset:         288
        .size:           8
        .value_kind:     hidden_global_offset_x
      - .offset:         296
        .size:           8
        .value_kind:     hidden_global_offset_y
      - .offset:         304
        .size:           8
        .value_kind:     hidden_global_offset_z
      - .offset:         312
        .size:           2
        .value_kind:     hidden_grid_dims
      - .offset:         368
        .size:           4
        .value_kind:     hidden_dynamic_lds_size
    .group_segment_fixed_size: 0
    .kernarg_segment_align: 8
    .kernarg_segment_size: 504
    .language:       OpenCL C
    .language_version:
      - 2
      - 0
    .max_flat_workgroup_size: 512
    .name:           _Z9hymba_fwd4Args
    .private_segment_fixed_size: 0
    .sgpr_count:     108
    .sgpr_spill_count: 26
    .symbol:         _Z9hymba_fwd4Args.kd
    .uniform_work_group_size: 1
    .uses_dynamic_stack: false
    .vgpr_count:     256
    .vgpr_spill_count: 0
    .wavefront_size: 64
